# strategy 7.5: packed v_pk_add/v_pk_fma f32 ops in attention tile loops split into scalar pairs (145 sites)
# baseline (speedup 1.0000x reference)
; #define LAS __attribute__((address_space(3)))
; DI unsigned pk2(float lo, float hi) { f32x2_t v = {lo, hi}; bf16x2_t b = __builtin_convertvector(v, bf16x2_t); return __builtin_bit_cast(unsigned, b); }
; DI float fexp2(float x) { return __builtin_amdgcn_exp2f(x); }
; #define MFMA32(a, b, c) __builtin_amdgcn_mfma_f32_32x32x16_bf16((a), (b), (c), 0, 0, 0)
; template <int MODE> DI void attn_h2(AttnCtx& c, f32x16 (&o)[4], f32x16& s0, f32x16& s1, ldsp lds, int vbuf, int tj, int lane) {
;     ...
;             } else {
;                 const float muse = (c.m == NINF) ? 0.f : c.m;
;                 float ps = 0.f;
; #pragma unroll
;                 for (int e = 0; e < 16; ++e) { s0[e] = fexp2(s0[e] - muse); s1[e] = fexp2(s1[e] - muse); ps += s0[e] + s1[e]; }
;                 c.l += ps;
;                         }
;             if (MODE != MD_CMP1) {
;                 ldsp vl = lds + vbuf + r32 * VPITCH + 16 * h;
; #pragma unroll
;                 for (int kb = 0; kb < 2; ++kb)
; #pragma unroll
;                     for (int s2 = 0; s2 < 2; ++s2) {
;                         u32x4 pw;
;                         if (kb == 0) { pw.x = pk2(s0[8 * s2], s0[8 * s2 + 1]); pw.y = pk2(s0[8 * s2 + 2], s0[8 * s2 + 3]); pw.z = pk2(s0[8 * s2 + 4], s0[8 * s2 + 5]); pw.w = pk2(s0[8 * s2 + 6], s0[8 * s2 + 7]); }
;                         else { pw.x = pk2(s1[8 * s2], s1[8 * s2 + 1]); pw.y = pk2(s1[8 * s2 + 2], s1[8 * s2 + 3]); pw.z = pk2(s1[8 * s2 + 4], s1[8 * s2 + 5]); pw.w = pk2(s1[8 * s2 + 6], s1[8 * s2 + 7]); }
;                         const bf16x8 pf = __builtin_bit_cast(bf16x8, pw);
; #pragma unroll
;                         for (int db = 0; db < 4; ++db) {
;                             const bf16x8 vf = *(const LAS bf16x8*)(vl + db * 32 * VPITCH + (kb * 2 + s2) * 32);
;                             o[db] = MFMA32(vf, pf, o[db]);
;                         }
;                     }
;             }
.LBB0_562:
	v_readlane_b32 s4, v254, 4
	v_readlane_b32 s5, v254, 5
	s_and_b64 s[8:9], s[4:5], s[8:9]
	s_and_saveexec_b64 s[4:5], s[8:9]
	s_cbranch_execz .LBB0_564
	v_cmp_neq_f32_e32 vcc, s53, v201
	s_mul_i32 s6, s7, 0x4800
	s_add_i32 s6, s6, 0x8800
	v_cndmask_b32_e32 v245, 0, v201, vcc
	v_sub_f32_e32 v0, v82, v245
	v_exp_f32_e32 v82, v0
	v_sub_f32_e32 v0, v98, v245
	v_exp_f32_e32 v98, v0
	v_sub_f32_e32 v0, v83, v245
	v_exp_f32_e32 v180, v0
	v_sub_f32_e32 v0, v99, v245
	v_exp_f32_e32 v0, v0
	v_sub_f32_e32 v83, v84, v245
	s_cmp_lg_u32 s7, 2
	v_exp_f32_e32 v84, v83
	v_sub_f32_e32 v83, v100, v245
	v_add_f32_e32 v181, v82, v98
	s_cselect_b32 s6, s6, 0x11a00
	v_exp_f32_e32 v100, v83
	v_add_f32_e64 v178, v180, v0
	v_add_f32_e64 v179, v181, v1
	v_sub_f32_e32 v83, v85, v245
	v_add_f32_e64 v179, v178, v179
	v_add_f32_e64 v178, v178, v178
	v_exp_f32_e32 v182, v83
	v_sub_f32_e32 v83, v101, v245
	v_add_u32_e32 v181, s6, v240
	v_exp_f32_e32 v178, v83
	v_sub_f32_e32 v83, v86, v245
	ds_read_b128 v[206:209], v181
	ds_read_b128 v[214:217], v181 offset:4608
	ds_read_b128 v[246:249], v181 offset:9216
	v_exp_f32_e32 v86, v83
	v_sub_f32_e32 v83, v87, v245
	v_exp_f32_e32 v184, v83
	v_sub_f32_e32 v83, v88, v245
	v_exp_f32_e32 v88, v83
	v_sub_f32_e32 v83, v89, v245
	v_exp_f32_e32 v204, v83
	v_sub_f32_e32 v83, v102, v245
	v_exp_f32_e32 v102, v83
	v_sub_f32_e32 v83, v90, v245
	v_cvt_pk_bf16_f32 v210, v82, v180
	v_cvt_pk_bf16_f32 v211, v84, v182
	v_cvt_pk_bf16_f32 v212, v86, v184
	v_cvt_pk_bf16_f32 v213, v88, v204
	v_exp_f32_e32 v90, v83
	v_sub_f32_e32 v83, v91, v245
	s_waitcnt lgkmcnt(0)
	v_mfma_f32_32x32x16_bf16 v[34:49], v[246:249], v[210:213], v[34:49]
	ds_read_b128 v[246:249], v181 offset:32
	v_add_f32_e32 v183, v84, v100
	v_add_f32_e64 v186, v182, v178
	v_add_f32_e64 v187, v183, v179
	ds_read_b128 v[224:227], v181 offset:13856
	v_add_f32_e64 v187, v186, v187
	v_add_f32_e64 v186, v186, v186
	v_add_f32_e32 v185, v86, v102
	v_mov_b32_e32 v85, v182
	v_mfma_f32_32x32x16_bf16 v[66:81], v[206:209], v[210:213], v[66:81]
	v_exp_f32_e32 v206, v83
	v_sub_f32_e32 v83, v92, v245
	v_exp_f32_e32 v92, v83
	v_sub_f32_e32 v83, v93, v245
	v_exp_f32_e32 v208, v83
	v_sub_f32_e32 v83, v94, v245
	v_exp_f32_e32 v94, v83
	v_mfma_f32_32x32x16_bf16 v[50:65], v[214:217], v[210:213], v[50:65]
	ds_read_b128 v[214:217], v181 offset:13824
	v_sub_f32_e32 v83, v95, v245
	v_exp_f32_e32 v202, v83
	v_sub_f32_e32 v83, v96, v245
	v_exp_f32_e32 v96, v83
	v_sub_f32_e32 v83, v97, v245
	v_exp_f32_e32 v97, v83
	s_waitcnt lgkmcnt(0)
	v_mfma_f32_32x32x16_bf16 v[16:31], v[214:217], v[210:213], v[16:31]
	v_cvt_pk_bf16_f32 v212, v90, v206
	v_cvt_pk_bf16_f32 v213, v92, v208
	v_cvt_pk_bf16_f32 v214, v94, v202
	v_cvt_pk_bf16_f32 v215, v96, v97
	v_sub_f32_e32 v83, v103, v245
	v_exp_f32_e32 v186, v83
	ds_read_b128 v[216:219], v181 offset:4640
	v_mfma_f32_32x32x16_bf16 v[66:81], v[246:249], v[212:215], v[66:81]
	ds_read_b128 v[246:249], v181 offset:9248
	v_add_f32_e64 v210, v184, v186
	v_add_f32_e64 v211, v185, v187
	v_sub_f32_e32 v83, v104, v245
	v_exp_f32_e32 v104, v83
	v_add_f32_e64 v211, v210, v211
	v_add_f32_e64 v210, v210, v210
	v_sub_f32_e32 v83, v105, v245
	v_exp_f32_e32 v210, v83
	s_waitcnt lgkmcnt(0)
	v_mfma_f32_32x32x16_bf16 v[34:49], v[246:249], v[212:215], v[34:49]
	ds_read_b128 v[246:249], v181 offset:64
	v_add_f32_e32 v205, v88, v104
	v_sub_f32_e32 v83, v106, v245
	v_exp_f32_e32 v106, v83
	v_sub_f32_e32 v83, v107, v245
	v_mov_b32_e32 v87, v184
	v_mov_b32_e32 v89, v204
	v_mfma_f32_32x32x16_bf16 v[16:31], v[224:227], v[212:215], v[16:31]
	v_cvt_pk_bf16_f32 v224, v98, v0
	v_cvt_pk_bf16_f32 v225, v100, v178
	v_cvt_pk_bf16_f32 v226, v102, v186
	v_cvt_pk_bf16_f32 v227, v104, v210
	v_add_f32_e32 v207, v90, v106
	ds_read_b128 v[182:185], v181 offset:9312
	v_mov_b32_e32 v95, v202
	v_mfma_f32_32x32x16_bf16 v[50:65], v[216:219], v[212:215], v[50:65]
	v_add_f32_e64 v216, v204, v210
	v_add_f32_e64 v217, v205, v211
	ds_read_b128 v[218:221], v181 offset:4672
	v_add_f32_e64 v217, v216, v217
	v_add_f32_e64 v216, v216, v216
	v_exp_f32_e32 v216, v83
	v_sub_f32_e32 v83, v108, v245
	v_exp_f32_e32 v108, v83
	v_sub_f32_e32 v83, v109, v245
	s_waitcnt lgkmcnt(2)
	v_mfma_f32_32x32x16_bf16 v[66:81], v[246:249], v[224:227], v[66:81]
	ds_read_b128 v[246:249], v181 offset:9280
	v_add_f32_e64 v212, v206, v216
	v_add_f32_e64 v213, v207, v217
	v_add_f32_e32 v209, v92, v108
	v_add_f32_e64 v213, v212, v213
	v_add_f32_e64 v212, v212, v212
	v_exp_f32_e32 v212, v83
	v_sub_f32_e32 v83, v110, v245
	v_exp_f32_e32 v110, v83
	s_waitcnt lgkmcnt(0)
	v_mfma_f32_32x32x16_bf16 v[34:49], v[246:249], v[224:227], v[34:49]
	ds_read_b128 v[246:249], v181 offset:96
	v_add_f32_e64 v214, v208, v212
	v_add_f32_e64 v215, v209, v213
	v_sub_f32_e32 v83, v111, v245
	v_add_f32_e64 v215, v214, v215
	v_add_f32_e64 v214, v214, v214
	v_exp_f32_e32 v214, v83
	v_add_f32_e32 v203, v94, v110
	v_sub_f32_e32 v83, v112, v245
	v_mfma_f32_32x32x16_bf16 v[50:65], v[218:221], v[224:227], v[50:65]
	ds_read_b128 v[220:223], v181 offset:13888
	v_add_f32_e64 v218, v202, v214
	v_add_f32_e64 v219, v203, v215
	ds_read_b128 v[202:205], v181 offset:13920
	v_exp_f32_e32 v112, v83
	v_sub_f32_e32 v83, v113, v245
	v_exp_f32_e32 v113, v83
	v_add_f32_e64 v219, v218, v219
	v_add_f32_e64 v218, v218, v218
	s_waitcnt lgkmcnt(1)
	v_mfma_f32_32x32x16_bf16 v[16:31], v[220:223], v[224:227], v[16:31]
	ds_read_b128 v[224:227], v181 offset:4704
	v_cvt_pk_bf16_f32 v220, v106, v216
	v_cvt_pk_bf16_f32 v221, v108, v212
	v_cvt_pk_bf16_f32 v222, v110, v214
	v_cvt_pk_bf16_f32 v223, v112, v113
	v_add_f32_e32 v179, v96, v112
	v_mov_b32_e32 v101, v178
	v_mfma_f32_32x32x16_bf16 v[66:81], v[246:249], v[220:223], v[66:81]
	v_mov_b32_e32 v178, v97
	v_mov_b32_e32 v218, v113
	v_add_f32_e64 v178, v178, v218
	v_add_f32_e64 v179, v179, v219
	v_mov_b32_e32 v99, v0
	v_add_f32_e32 v0, v178, v179
	v_mov_b32_e32 v83, v180
	v_mov_b32_e32 v91, v206
	s_waitcnt lgkmcnt(0)
	v_mfma_f32_32x32x16_bf16 v[50:65], v[224:227], v[220:223], v[50:65]
	v_mov_b32_e32 v93, v208
	v_mov_b32_e32 v103, v186
	v_mov_b32_e32 v105, v210
	v_mov_b32_e32 v107, v216
	v_mov_b32_e32 v109, v212
	v_mov_b32_e32 v111, v214
	v_add_f32_e32 v32, v32, v0
	v_mfma_f32_32x32x16_bf16 v[34:49], v[182:185], v[220:223], v[34:49]
	v_mfma_f32_32x32x16_bf16 v[16:31], v[202:205], v[220:223], v[16:31]
; #define LAS __attribute__((address_space(3)))
; #define MFMA32(a, b, c) __builtin_amdgcn_mfma_f32_32x32x16_bf16((a), (b), (c), 0, 0, 0)
; template <int MODE> DI void attn_h1(AttnCtx& c, const bf16x8 (&q)[8], f32x16 (&o)[4], f32x16& s0, f32x16& s1, ldsp lds, int kbuf, int bbuf, int tj, int lane) {
;     const int r32 = lane & 31, h = lane >> 5;
;             ldsp kl = lds + kbuf + r32 * KPITCH + h * 16;
; #pragma unroll
;             for (int e = 0; e < 16; ++e) { s0[e] = 0.f; s1[e] = 0.f; }
; #pragma unroll
;             for (int s = 0; s < 8; ++s) {
;                 const bf16x8 ka = *(const LAS bf16x8*)(kl + s * 32), kb = *(const LAS bf16x8*)(kl + 32 * KPITCH + s * 32);
;                 s0 = MFMA32(ka, q[s], s0); s1 = MFMA32(kb, q[s], s1);
;                 if (s == 3) asm volatile("" ::: "memory");
;             }
;             const float NINF = -__builtin_inff();
;             if (MODE == MD_FOX) {
;                 const LAS float* bl = (const LAS float*)(lds + A_BIAS + bbuf);
;                 const int kbase = tj * 64 + 4 * h;
;                 const bool needmask = tj >= c.whi;
; #pragma unroll
;                 for (int g4 = 0; g4 < 4; ++g4) {
;                     const f32x4 b0 = *(const LAS f32x4*)(bl + 8 * g4 + 4 * h), b1 = *(const LAS f32x4*)(bl + 32 + 8 * g4 + 4 * h);
; #pragma unroll
;                     for (int e = 0; e < 4; ++e) { s0[4 * g4 + e] += b0[e]; s1[4 * g4 + e] += b1[e]; }
;                 }
.LBB0_564:
	s_or_b64 exec, exec, s[4:5]
	v_cmp_le_i32_e32 vcc, s95, v242
	s_and_b32 s21, s96, 1
	s_and_b64 s[22:23], vcc, s[2:3]
	s_and_saveexec_b64 s[24:25], s[22:23]
	s_cbranch_execz .LBB0_569
	s_mul_i32 s2, s21, 0x4400
	v_add_u32_e32 v0, s2, v237
	ds_read_b128 v[98:101], v0 offset:8704
	ds_read_b128 v[82:85], v0
	ds_read_b128 v[178:181], v0 offset:32
	ds_read_b128 v[182:185], v0 offset:8736
	v_cmp_ge_i32_e32 vcc, s95, v242
	s_waitcnt lgkmcnt(3)
	v_mfma_f32_32x32x16_bf16 v[98:113], v[98:101], v[136:139], 0
	s_waitcnt lgkmcnt(2)
	v_mfma_f32_32x32x16_bf16 v[82:97], v[82:85], v[136:139], 0
	s_waitcnt lgkmcnt(1)
	v_mfma_f32_32x32x16_bf16 v[82:97], v[178:181], v[140:143], v[82:97]
	s_waitcnt lgkmcnt(0)
	v_mfma_f32_32x32x16_bf16 v[98:113], v[182:185], v[140:143], v[98:113]
	ds_read_b128 v[178:181], v0 offset:8768
	ds_read_b128 v[182:185], v0 offset:64
	s_waitcnt lgkmcnt(0)
	v_mfma_f32_32x32x16_bf16 v[82:97], v[182:185], v[144:147], v[82:97]
	v_mfma_f32_32x32x16_bf16 v[98:113], v[178:181], v[144:147], v[98:113]
	ds_read_b128 v[178:181], v0 offset:8800
	ds_read_b128 v[182:185], v0 offset:96
	s_waitcnt lgkmcnt(0)
	v_mfma_f32_32x32x16_bf16 v[82:97], v[182:185], v[148:151], v[82:97]
	v_mfma_f32_32x32x16_bf16 v[98:113], v[178:181], v[148:151], v[98:113]
	ds_read_b128 v[178:181], v0 offset:8832
	ds_read_b128 v[182:185], v0 offset:128
	ds_read_b128 v[202:205], v0 offset:160
	s_waitcnt lgkmcnt(1)
	v_mfma_f32_32x32x16_bf16 v[82:97], v[182:185], v[152:155], v[82:97]
	v_mfma_f32_32x32x16_bf16 v[98:113], v[178:181], v[152:155], v[98:113]
	ds_read_b128 v[178:181], v0 offset:8864
	s_waitcnt lgkmcnt(1)
	v_mfma_f32_32x32x16_bf16 v[82:97], v[202:205], v[156:159], v[82:97]
	s_waitcnt lgkmcnt(0)
	v_mfma_f32_32x32x16_bf16 v[98:113], v[178:181], v[156:159], v[98:113]
	ds_read_b128 v[178:181], v0 offset:8896
	ds_read_b128 v[182:185], v0 offset:192
	s_waitcnt lgkmcnt(0)
	v_mfma_f32_32x32x16_bf16 v[82:97], v[182:185], v[160:163], v[82:97]
	v_mfma_f32_32x32x16_bf16 v[98:113], v[178:181], v[160:163], v[98:113]
	ds_read_b128 v[178:181], v0 offset:8928
	ds_read_b128 v[182:185], v0 offset:224
	v_lshl_add_u32 v0, s21, 8, v243
	s_waitcnt lgkmcnt(0)
	v_mfma_f32_32x32x16_bf16 v[82:97], v[182:185], v[164:167], v[82:97]
	v_mfma_f32_32x32x16_bf16 v[98:113], v[178:181], v[164:167], v[98:113]
	ds_read_b128 v[178:181], v0
	ds_read_b128 v[182:185], v0 offset:32
	ds_read_b128 v[202:205], v0 offset:128
	s_waitcnt lgkmcnt(2)
	s_nop 6
	v_add_f32_e64 v82, v82, v178
	v_add_f32_e64 v83, v83, v179
	v_add_f32_e64 v84, v84, v180
	v_add_f32_e64 v85, v85, v181
	ds_read_b128 v[178:181], v0 offset:160
	s_waitcnt lgkmcnt(2)
	v_add_f32_e64 v86, v86, v182
	v_add_f32_e64 v87, v87, v183
	v_add_f32_e64 v88, v88, v184
	v_add_f32_e64 v89, v89, v185
	s_waitcnt lgkmcnt(1)
	v_add_f32_e64 v98, v98, v202
	v_add_f32_e64 v99, v99, v203
	v_add_f32_e64 v100, v100, v204
	v_add_f32_e64 v101, v101, v205
	s_waitcnt lgkmcnt(0)
	v_add_f32_e64 v102, v102, v178
	v_add_f32_e64 v103, v103, v179
	v_add_f32_e64 v104, v104, v180
	v_add_f32_e64 v105, v105, v181
	ds_read_b128 v[178:181], v0 offset:64
	ds_read_b128 v[182:185], v0 offset:192
	s_waitcnt lgkmcnt(1)
	v_add_f32_e64 v90, v90, v178
	v_add_f32_e64 v91, v91, v179
	s_waitcnt lgkmcnt(0)
	v_add_f32_e64 v106, v106, v182
	v_add_f32_e64 v107, v107, v183
	v_add_f32_e64 v92, v92, v180
	v_add_f32_e64 v93, v93, v181
	v_add_f32_e64 v108, v108, v184
	v_add_f32_e64 v109, v109, v185
	ds_read_b128 v[178:181], v0 offset:96
	ds_read_b128 v[182:185], v0 offset:224
	s_waitcnt lgkmcnt(1)
	v_add_f32_e64 v94, v94, v178
	v_add_f32_e64 v95, v95, v179
	s_waitcnt lgkmcnt(0)
	v_add_f32_e64 v110, v110, v182
	v_add_f32_e64 v111, v111, v183
	v_add_f32_e64 v96, v96, v180
	v_add_f32_e64 v97, v97, v181
	v_add_f32_e64 v112, v112, v184
	v_add_f32_e64 v113, v113, v185
	s_and_saveexec_b64 s[26:27], vcc
	s_cbranch_execz .LBB0_567
; template <int MODE> DI void attn_h1(AttnCtx& c, const bf16x8 (&q)[8], f32x16 (&o)[4], f32x16& s0, f32x16& s1, ldsp lds, int kbuf, int bbuf, int tj, int lane) {
;     ...
;                 if (needmask) {
; #pragma unroll
;                     for (int e = 0; e < 16; ++e) {
;                         const int k0 = kbase + 8 * (e >> 2) + (e & 3);
;                         s0[e] = (k0 <= c.t) ? s0[e] : NINF; s1[e] = (k0 + 32 <= c.t) ? s1[e] : NINF;
;                     }
;                 }
	v_or_b32_e32 v0, 3, v244
	v_cmp_le_i32_e32 vcc, v0, v115
	v_or_b32_e32 v0, 2, v244
	v_cmp_le_i32_e64 s[2:3], v0, v196
	v_or_b32_e32 v0, 9, v244
	v_cmp_le_i32_e64 s[4:5], v0, v115
	v_or_b32_e32 v0, 8, v244
	v_cmp_le_i32_e64 s[6:7], v0, v196
	v_or_b32_e32 v0, 11, v244
	v_cmp_le_i32_e64 s[8:9], v0, v115
	v_or_b32_e32 v0, 10, v244
	v_cmp_le_i32_e64 s[10:11], v0, v196
	v_or_b32_e32 v0, 17, v244
	v_cmp_le_i32_e64 s[12:13], v0, v115
	v_or_b32_e32 v0, 16, v244
	v_cmp_le_i32_e64 s[14:15], v0, v196
	v_or_b32_e32 v0, 19, v244
	v_cmp_le_i32_e64 s[48:49], v0, v115
	v_or_b32_e32 v0, 18, v244
	v_cmp_le_i32_e64 s[50:51], v0, v196
	v_or_b32_e32 v0, 25, v244
	v_cmp_le_i32_e64 s[52:53], v0, v115
	v_or_b32_e32 v0, 24, v244
	v_cmp_le_i32_e64 s[54:55], v0, v196
	v_or_b32_e32 v0, 27, v244
	v_cmp_le_i32_e64 s[56:57], v0, v115
	v_or_b32_e32 v0, 26, v244
	v_cmp_le_i32_e64 s[58:59], v0, v196
	v_or_b32_e32 v0, 59, v244
	v_cmp_le_i32_e64 s[60:61], v0, v33
	v_or_b32_e32 v0, 58, v244
	v_cmp_le_i32_e64 s[62:63], v0, v114
	v_or_b32_e32 v0, 57, v244
	v_cmp_le_i32_e64 s[64:65], v0, v15
	v_or_b32_e32 v0, 56, v244
	v_cmp_le_i32_e64 s[66:67], v0, v14
	v_or_b32_e32 v0, 51, v244
	v_cmp_le_i32_e64 s[68:69], v0, v13
	v_or_b32_e32 v0, 50, v244
	v_cmp_le_i32_e64 s[70:71], v0, v12
	v_or_b32_e32 v0, 49, v244
	v_cmp_le_i32_e64 s[72:73], v0, v11
	v_or_b32_e32 v0, 48, v244
	v_cmp_le_i32_e64 s[74:75], v0, v10
	v_or_b32_e32 v0, 43, v244
	v_cmp_le_i32_e64 s[76:77], v0, v9
	v_or_b32_e32 v0, 42, v244
	v_cmp_le_i32_e64 s[78:79], v0, v8
	v_or_b32_e32 v0, 41, v244
	v_cmp_le_i32_e64 s[80:81], v0, v7
	v_or_b32_e32 v0, 40, v244
	v_cmp_le_i32_e64 s[82:83], v0, v6
	v_or_b32_e32 v0, 35, v244
	v_cmp_le_i32_e64 s[84:85], v0, v5
	v_or_b32_e32 v0, 34, v244
	v_cmp_le_i32_e64 s[86:87], v0, v4
	v_or_b32_e32 v0, 33, v244
	v_cmp_le_i32_e64 s[88:89], v0, v3
	v_or_b32_e32 v0, 32, v244
	v_cmp_le_i32_e64 s[92:93], v244, v196
	v_cmp_le_i32_e64 s[90:91], v0, v2
	v_cndmask_b32_e64 v103, v230, v103, s[80:81]
	v_cndmask_b32_e64 v82, v230, v82, s[92:93]
	v_cmp_lt_i32_e64 s[92:93], v244, v196
	v_readlane_b32 s80, v254, 38
	v_cndmask_b32_e32 v85, v230, v85, vcc
	v_cndmask_b32_e64 v83, v230, v83, s[92:93]
	v_cndmask_b32_e64 v84, v230, v84, s[2:3]
	v_cndmask_b32_e64 v87, v230, v87, s[4:5]
	v_cndmask_b32_e64 v86, v230, v86, s[6:7]
	v_cndmask_b32_e64 v89, v230, v89, s[8:9]
	v_cndmask_b32_e64 v88, v230, v88, s[10:11]
	v_cndmask_b32_e64 v91, v230, v91, s[12:13]
	v_cndmask_b32_e64 v90, v230, v90, s[14:15]
	v_cndmask_b32_e64 v93, v230, v93, s[48:49]
	v_cndmask_b32_e64 v92, v230, v92, s[50:51]
	v_cndmask_b32_e64 v95, v230, v95, s[52:53]
	s_mov_b32 s53, 0xff800000
	s_mov_b32 s52, 0x800000
	v_cndmask_b32_e64 v94, v230, v94, s[54:55]
	v_cndmask_b32_e64 v97, v230, v97, s[56:57]
	v_cndmask_b32_e64 v96, v230, v96, s[58:59]
	v_cndmask_b32_e64 v113, v230, v113, s[60:61]
	v_cndmask_b32_e64 v112, v230, v112, s[62:63]
	v_cndmask_b32_e64 v111, v230, v111, s[64:65]
	v_cndmask_b32_e64 v110, v230, v110, s[66:67]
	v_cndmask_b32_e64 v109, v230, v109, s[68:69]
	v_cndmask_b32_e64 v108, v230, v108, s[70:71]
	v_cndmask_b32_e64 v107, v230, v107, s[72:73]
	v_cndmask_b32_e64 v106, v230, v106, s[74:75]
	v_cndmask_b32_e64 v105, v230, v105, s[76:77]
	v_cndmask_b32_e64 v104, v230, v104, s[78:79]
	v_cndmask_b32_e64 v102, v230, v102, s[82:83]
	v_cndmask_b32_e64 v101, v230, v101, s[84:85]
	v_cndmask_b32_e64 v100, v230, v100, s[86:87]
	v_cndmask_b32_e64 v99, v230, v99, s[88:89]
	v_readlane_b32 s81, v254, 39
	v_cndmask_b32_e64 v98, v230, v98, s[90:91]

; #define LAS __attribute__((address_space(3)))
; DI unsigned pk2(float lo, float hi) { f32x2_t v = {lo, hi}; bf16x2_t b = __builtin_convertvector(v, bf16x2_t); return __builtin_bit_cast(unsigned, b); }
; DI float fexp2(float x) { return __builtin_amdgcn_exp2f(x); }
; #define MFMA32(a, b, c) __builtin_amdgcn_mfma_f32_32x32x16_bf16((a), (b), (c), 0, 0, 0)
; template <int MODE> DI void attn_h2(AttnCtx& c, f32x16 (&o)[4], f32x16& s0, f32x16& s1, ldsp lds, int vbuf, int tj, int lane) {
;     ...
;             } else {
;                 const float muse = (c.m == NINF) ? 0.f : c.m;
;                 float ps = 0.f;
; #pragma unroll
;                 for (int e = 0; e < 16; ++e) { s0[e] = fexp2(s0[e] - muse); s1[e] = fexp2(s1[e] - muse); ps += s0[e] + s1[e]; }
;                 c.l += ps;
;                         }
;             if (MODE != MD_CMP1) {
;                 ldsp vl = lds + vbuf + r32 * VPITCH + 16 * h;
; #pragma unroll
;                 for (int kb = 0; kb < 2; ++kb)
; #pragma unroll
;                     for (int s2 = 0; s2 < 2; ++s2) {
;                         u32x4 pw;
;                         if (kb == 0) { pw.x = pk2(s0[8 * s2], s0[8 * s2 + 1]); pw.y = pk2(s0[8 * s2 + 2], s0[8 * s2 + 3]); pw.z = pk2(s0[8 * s2 + 4], s0[8 * s2 + 5]); pw.w = pk2(s0[8 * s2 + 6], s0[8 * s2 + 7]); }
;                         else { pw.x = pk2(s1[8 * s2], s1[8 * s2 + 1]); pw.y = pk2(s1[8 * s2 + 2], s1[8 * s2 + 3]); pw.z = pk2(s1[8 * s2 + 4], s1[8 * s2 + 5]); pw.w = pk2(s1[8 * s2 + 6], s1[8 * s2 + 7]); }
;                         const bf16x8 pf = __builtin_bit_cast(bf16x8, pw);
; #pragma unroll
;                         for (int db = 0; db < 4; ++db) {
;                             const bf16x8 vf = *(const LAS bf16x8*)(vl + db * 32 * VPITCH + (kb * 2 + s2) * 32);
;                             o[db] = MFMA32(vf, pf, o[db]);
;                         }
;                     }
;             }
.LBB0_569:
	s_or_b64 exec, exec, s[24:25]
	v_readlane_b32 s4, v254, 6
	s_cmp_eq_u32 s20, 2
	v_readlane_b32 s5, v254, 7
	s_cselect_b64 s[2:3], -1, 0
	s_and_b64 s[6:7], s[22:23], s[4:5]
	s_and_saveexec_b64 s[4:5], s[6:7]
	s_cbranch_execz .LBB0_571
	v_cmp_neq_f32_e32 vcc, s53, v201
	s_mul_i32 s6, s20, 0x4800
	s_add_i32 s8, s6, 0x8800
	v_cndmask_b32_e32 v216, 0, v201, vcc
	v_sub_f32_e32 v0, v82, v216
	v_exp_f32_e32 v82, v0
	v_sub_f32_e32 v0, v98, v216
	v_exp_f32_e32 v98, v0
	v_sub_f32_e32 v0, v83, v216
	v_sub_f32_e32 v83, v99, v216
	v_exp_f32_e32 v0, v0
	v_exp_f32_e32 v178, v83
	v_add_f32_e32 v179, v98, v82
	v_sub_f32_e32 v83, v84, v216
	v_exp_f32_e32 v84, v83
	v_add_f32_e64 v180, v178, v0
	v_add_f32_e64 v181, v179, v1
	v_sub_f32_e32 v83, v100, v216
	v_add_f32_e64 v184, v180, v180
	v_add_f32_e64 v185, v180, v181
	v_exp_f32_e32 v100, v83
	v_sub_f32_e32 v83, v85, v216
	v_exp_f32_e32 v184, v83
	v_sub_f32_e32 v83, v101, v216
	v_exp_f32_e32 v180, v83
	v_add_f32_e32 v181, v100, v84
	v_sub_f32_e32 v83, v86, v216
	v_exp_f32_e32 v86, v83
	v_add_f32_e64 v182, v180, v184
	v_add_f32_e64 v183, v181, v185
	v_sub_f32_e32 v83, v102, v216
	v_add_f32_e64 v202, v182, v182
	v_add_f32_e64 v203, v182, v183
	v_exp_f32_e32 v102, v83
	v_sub_f32_e32 v83, v87, v216
	v_exp_f32_e32 v202, v83
	v_sub_f32_e32 v83, v103, v216
	v_exp_f32_e32 v182, v83
	v_add_f32_e32 v183, v102, v86
	v_sub_f32_e32 v83, v88, v216
	v_exp_f32_e32 v88, v83
	v_add_f32_e64 v186, v182, v202
	v_add_f32_e64 v187, v183, v203
	v_sub_f32_e32 v83, v104, v216
	s_and_b64 s[6:7], s[2:3], exec
	v_add_f32_e64 v206, v186, v186
	v_add_f32_e64 v207, v186, v187
	v_exp_f32_e32 v104, v83
	v_sub_f32_e32 v83, v89, v216
	s_cselect_b32 s6, 0x11a00, s8
	v_exp_f32_e32 v206, v83
	v_sub_f32_e32 v83, v105, v216
	v_add_u32_e32 v179, s6, v240
	v_exp_f32_e32 v186, v83
	ds_read_b128 v[222:225], v179 offset:4608
	ds_read_b128 v[246:249], v179 offset:9216
	v_add_f32_e32 v187, v104, v88
	v_sub_f32_e32 v83, v90, v216
	v_add_f32_e64 v204, v186, v206
	v_add_f32_e64 v205, v187, v207
	v_exp_f32_e32 v90, v83
	v_sub_f32_e32 v83, v106, v216
	v_add_f32_e64 v208, v204, v204
	v_add_f32_e64 v209, v204, v205
	v_exp_f32_e32 v106, v83
	v_sub_f32_e32 v83, v91, v216
	ds_read_b128 v[210:213], v179
	v_exp_f32_e32 v208, v83
	v_sub_f32_e32 v83, v107, v216
	v_exp_f32_e32 v204, v83
	v_cvt_pk_bf16_f32 v218, v82, v0
	v_cvt_pk_bf16_f32 v219, v84, v184
	v_cvt_pk_bf16_f32 v220, v86, v202
	v_cvt_pk_bf16_f32 v221, v88, v206
	v_add_f32_e32 v205, v106, v90
	v_sub_f32_e32 v83, v92, v216
	s_waitcnt lgkmcnt(2)
	v_mfma_f32_32x32x16_bf16 v[50:65], v[222:225], v[218:221], v[50:65]
	ds_read_b128 v[222:225], v179 offset:13824
	v_add_f32_e64 v214, v204, v208
	v_add_f32_e64 v215, v205, v209
	v_exp_f32_e32 v92, v83
	v_sub_f32_e32 v83, v108, v216
	v_add_f32_e64 v215, v214, v215
	v_add_f32_e64 v214, v214, v214
	v_exp_f32_e32 v108, v83
	v_sub_f32_e32 v83, v93, v216
	v_exp_f32_e32 v214, v83
	v_sub_f32_e32 v83, v109, v216
	s_waitcnt lgkmcnt(2)
	v_mfma_f32_32x32x16_bf16 v[34:49], v[246:249], v[218:221], v[34:49]
	ds_read_b128 v[246:249], v179 offset:32
	v_mov_b32_e32 v89, v206
	v_mov_b32_e32 v91, v208
	v_mov_b32_e32 v99, v178
	v_mov_b32_e32 v101, v180
	v_mov_b32_e32 v103, v182
	v_mov_b32_e32 v85, v184
	s_waitcnt lgkmcnt(2)
	v_mfma_f32_32x32x16_bf16 v[66:81], v[210:213], v[218:221], v[66:81]
	v_exp_f32_e32 v210, v83
	v_add_f32_e32 v211, v108, v92
	v_sub_f32_e32 v83, v94, v216
	v_exp_f32_e32 v94, v83
	v_add_f32_e64 v212, v210, v214
	v_add_f32_e64 v213, v211, v215
	v_sub_f32_e32 v83, v95, v216
	v_add_f32_e64 v213, v212, v213
	v_add_f32_e64 v212, v212, v212
	s_waitcnt lgkmcnt(1)
	v_mfma_f32_32x32x16_bf16 v[16:31], v[222:225], v[218:221], v[16:31]
	ds_read_b128 v[222:225], v179 offset:4640
	v_exp_f32_e32 v212, v83
	v_sub_f32_e32 v83, v96, v216
	v_exp_f32_e32 v96, v83
	v_sub_f32_e32 v83, v97, v216
	v_exp_f32_e32 v97, v83
	v_cvt_pk_bf16_f32 v218, v90, v208
	v_cvt_pk_bf16_f32 v219, v92, v214
	v_cvt_pk_bf16_f32 v220, v94, v212
	v_cvt_pk_bf16_f32 v221, v96, v97
	v_sub_f32_e32 v83, v110, v216
	v_exp_f32_e32 v110, v83
	s_waitcnt lgkmcnt(1)
	v_mfma_f32_32x32x16_bf16 v[66:81], v[246:249], v[218:221], v[66:81]
	ds_read_b128 v[246:249], v179 offset:13888
	v_sub_f32_e32 v83, v111, v216
	v_exp_f32_e32 v226, v83
	v_add_f32_e32 v227, v110, v94
	ds_read_b128 v[206:209], v179 offset:9312
	v_sub_f32_e32 v83, v112, v216
	v_exp_f32_e32 v112, v83
	s_waitcnt lgkmcnt(2)
	v_mfma_f32_32x32x16_bf16 v[50:65], v[222:225], v[218:221], v[50:65]
	ds_read_b128 v[222:225], v179 offset:9248
	v_sub_f32_e32 v83, v113, v216
	v_exp_f32_e32 v113, v83
	v_add_f32_e32 v183, v112, v96
	v_mov_b32_e32 v83, v0
	v_mov_b32_e32 v87, v202
	v_mov_b32_e32 v93, v214
	s_waitcnt lgkmcnt(0)
	v_mfma_f32_32x32x16_bf16 v[34:49], v[222:225], v[218:221], v[34:49]
	ds_read_b128 v[222:225], v179 offset:13856
	v_mov_b32_e32 v95, v212
	v_mov_b32_e32 v105, v186
	v_mov_b32_e32 v107, v204
	v_mov_b32_e32 v109, v210
	v_mov_b32_e32 v111, v226
	s_waitcnt lgkmcnt(0)
	v_mfma_f32_32x32x16_bf16 v[16:31], v[222:225], v[218:221], v[16:31]
	ds_read_b128 v[218:221], v179 offset:64
	v_cvt_pk_bf16_f32 v222, v98, v178
	v_cvt_pk_bf16_f32 v223, v100, v180
	v_cvt_pk_bf16_f32 v224, v102, v182
	v_cvt_pk_bf16_f32 v225, v104, v186
	v_mov_b32_e32 v182, v113
	s_nop 0
	v_mfma_f32_32x32x16_bf16 v[16:31], v[246:249], v[222:225], v[16:31]
	ds_read_b128 v[246:249], v179 offset:4704
	s_waitcnt lgkmcnt(1)
	v_mfma_f32_32x32x16_bf16 v[66:81], v[218:221], v[222:225], v[66:81]
	ds_read_b128 v[218:221], v179 offset:4672
	s_waitcnt lgkmcnt(0)
	v_mfma_f32_32x32x16_bf16 v[50:65], v[218:221], v[222:225], v[50:65]
	ds_read_b128 v[218:221], v179 offset:9280
	s_waitcnt lgkmcnt(0)
	v_mfma_f32_32x32x16_bf16 v[34:49], v[218:221], v[222:225], v[34:49]
	v_add_f32_e64 v218, v226, v212
	v_add_f32_e64 v219, v227, v213
	v_cvt_pk_bf16_f32 v222, v106, v204
	v_add_f32_e64 v250, v218, v218
	v_add_f32_e64 v251, v218, v219
	ds_read_b128 v[218:221], v179 offset:96
	ds_read_b128 v[178:181], v179 offset:13920
	v_cvt_pk_bf16_f32 v223, v108, v210
	v_cvt_pk_bf16_f32 v224, v110, v226
	v_cvt_pk_bf16_f32 v225, v112, v113
	v_mov_b32_e32 v250, v97
	v_add_f32_e64 v182, v182, v250
	v_add_f32_e64 v183, v183, v251
	s_waitcnt lgkmcnt(1)
	v_mfma_f32_32x32x16_bf16 v[66:81], v[218:221], v[222:225], v[66:81]
	v_add_f32_e32 v0, v182, v183
	v_add_f32_e32 v32, v32, v0
	v_mfma_f32_32x32x16_bf16 v[50:65], v[246:249], v[222:225], v[50:65]
	v_mfma_f32_32x32x16_bf16 v[34:49], v[206:209], v[222:225], v[34:49]
	s_waitcnt lgkmcnt(0)
	v_mfma_f32_32x32x16_bf16 v[16:31], v[178:181], v[222:225], v[16:31]

; template <int MODE> DI void attn_run(AttnCtx& c, const bf16x8 (&q)[8], f32x16 (&o)[4], ldsp lds, int tid, int wv) {
;     ...
;         if (MODE == MD_FOX || ((MODE == MD_SEL || MODE == MD_CMP1 || MODE == MD_CMP2) && c.xsel)) {
;             const bool needs = (cb_next + c.bqk >= c.m - 32.0f);
;             const unsigned wn = (__ballot(needs) != 0ull) ? 1u : 0u;
;             wneed = (wn != 0u);
;             if (lane == 0) xflag[(i & 1) * NWAVES + wv] = wn;
;         }
;         __syncthreads();
.LBB0_575:
	s_waitcnt vmcnt(0)
	v_add_f32_e64 v178, v190, v200
	v_add_f32_e64 v179, v191, v201
	s_nop 0
	v_cmp_ge_f32_e32 vcc, v178, v179
	s_cmp_lg_u64 vcc, 0
	s_cselect_b64 s[2:3], -1, 0
	s_and_saveexec_b64 s[4:5], s[42:43]
	s_lshl_b32 s7, s21, 5
	s_add_i32 s7, s28, s7
	v_cndmask_b32_e64 v0, 0, 1, s[2:3]
	v_mov_b32_e32 v178, s7
	ds_write_b32 v178, v0
	s_or_b64 exec, exec, s[4:5]
	s_andn2_b64 s[4:5], s[18:19], exec
	s_and_b64 s[8:9], s[22:23], exec
	s_or_b64 s[8:9], s[4:5], s[8:9]
	s_mov_b32 s7, s20
	s_waitcnt lgkmcnt(0)
	s_barrier
	s_branch .LBB0_579

; #define LAS __attribute__((address_space(3)))
; #define MFMA32(a, b, c) __builtin_amdgcn_mfma_f32_32x32x16_bf16((a), (b), (c), 0, 0, 0)
; template <int MODE> DI void attn_h1(AttnCtx& c, const bf16x8 (&q)[8], f32x16 (&o)[4], f32x16& s0, f32x16& s1, ldsp lds, int kbuf, int bbuf, int tj, int lane) {
;     const int r32 = lane & 31, h = lane >> 5;
;             ldsp kl = lds + kbuf + r32 * KPITCH + h * 16;
; #pragma unroll
;             for (int e = 0; e < 16; ++e) { s0[e] = 0.f; s1[e] = 0.f; }
; #pragma unroll
;             for (int s = 0; s < 8; ++s) {
;                 const bf16x8 ka = *(const LAS bf16x8*)(kl + s * 32), kb = *(const LAS bf16x8*)(kl + 32 * KPITCH + s * 32);
;                 s0 = MFMA32(ka, q[s], s0); s1 = MFMA32(kb, q[s], s1);
;                 if (s == 3) asm volatile("" ::: "memory");
;             }
;     ...
;                 if (needmask) {
; #pragma unroll
;                     for (int e = 0; e < 16; ++e) {
;                         const float d0 = dbase - (float)(PS * (8 * (e >> 2) + (e & 3))), d1 = d0 - (float)(PS * 32);
;                         bool v0 = d0 >= 0.f, v1 = d1 >= 0.f;
;                         if (MODE == MD_WIN) { v0 = v0 && d0 < 512.f; v1 = v1 && d1 < 512.f; }
;                         if (MODE == MD_SEL) { v0 = v0 && selbit; v1 = v1 && selbit; }
;                         s0[e] = v0 ? s0[e] - c.slope2 * d0 : NINF;
;                         s1[e] = v1 ? s1[e] - c.slope2 * d1 : NINF;
;                     }
.LBB0_614:
	s_mul_i32 s29, s28, 0x4400
	v_add_u32_e32 v0, s29, v205
	ds_read_b128 v[2:5], v0
	ds_read_b128 v[80:83], v0 offset:32
	s_mov_b32 s29, 0xff800000
	s_mov_b32 s25, 0xff800000
	s_waitcnt lgkmcnt(1)
	v_mfma_f32_32x32x16_bf16 v[18:33], v[2:5], v[98:101], 0
	ds_read_b128 v[2:5], v0 offset:8704
	s_waitcnt lgkmcnt(1)
	v_mfma_f32_32x32x16_bf16 v[18:33], v[80:83], v[102:105], v[18:33]
	ds_read_b128 v[80:83], v0 offset:8736
	s_waitcnt lgkmcnt(1)
	v_mfma_f32_32x32x16_bf16 v[2:17], v[2:5], v[98:101], 0
	s_waitcnt lgkmcnt(0)
	v_mfma_f32_32x32x16_bf16 v[2:17], v[80:83], v[102:105], v[2:17]
	ds_read_b128 v[80:83], v0 offset:64
	s_waitcnt lgkmcnt(0)
	v_mfma_f32_32x32x16_bf16 v[18:33], v[80:83], v[106:109], v[18:33]
	ds_read_b128 v[80:83], v0 offset:8768
	s_waitcnt lgkmcnt(0)
	v_mfma_f32_32x32x16_bf16 v[2:17], v[80:83], v[106:109], v[2:17]
	ds_read_b128 v[80:83], v0 offset:96
	s_waitcnt lgkmcnt(0)
	v_mfma_f32_32x32x16_bf16 v[18:33], v[80:83], v[110:113], v[18:33]
	ds_read_b128 v[80:83], v0 offset:8800
	s_waitcnt lgkmcnt(0)
	v_mfma_f32_32x32x16_bf16 v[2:17], v[80:83], v[110:113], v[2:17]
	ds_read_b128 v[80:83], v0 offset:128
	s_waitcnt lgkmcnt(0)
	v_mfma_f32_32x32x16_bf16 v[18:33], v[80:83], v[114:117], v[18:33]
	ds_read_b128 v[80:83], v0 offset:8832
	s_waitcnt lgkmcnt(0)
	v_mfma_f32_32x32x16_bf16 v[2:17], v[80:83], v[114:117], v[2:17]
	ds_read_b128 v[80:83], v0 offset:160
	s_waitcnt lgkmcnt(0)
	v_mfma_f32_32x32x16_bf16 v[18:33], v[80:83], v[118:121], v[18:33]
	ds_read_b128 v[80:83], v0 offset:8864
	s_waitcnt lgkmcnt(0)
	v_mfma_f32_32x32x16_bf16 v[2:17], v[80:83], v[118:121], v[2:17]
	ds_read_b128 v[80:83], v0 offset:192
	s_waitcnt lgkmcnt(0)
	v_mfma_f32_32x32x16_bf16 v[18:33], v[80:83], v[122:125], v[18:33]
	ds_read_b128 v[80:83], v0 offset:8896
	s_waitcnt lgkmcnt(0)
	v_mfma_f32_32x32x16_bf16 v[2:17], v[80:83], v[122:125], v[2:17]
	ds_read_b128 v[80:83], v0 offset:224
	ds_read_b128 v[84:87], v0 offset:8928
	v_add3_u32 v0, v172, v79, -16
	v_cmp_lt_i32_e32 vcc, -1, v0
	s_waitcnt lgkmcnt(1)
	v_mfma_f32_32x32x16_bf16 v[18:33], v[80:83], v[126:129], v[18:33]
	v_cvt_f32_i32_e32 v80, v0
	v_add_f32_e32 v81, 0xc4000000, v80
	s_waitcnt lgkmcnt(0)
	v_mfma_f32_32x32x16_bf16 v[2:17], v[84:87], v[126:129], v[2:17]
	s_nop 7
	v_fma_f32 v18, -v146, v80, v18
	v_cndmask_b32_e32 v0, v230, v18, vcc
	v_cmp_le_f32_e32 vcc, 0, v81
	v_add_f32_e32 v18, 0xc1800000, v80
	v_fma_f32 v19, -v146, v18, v19
	v_fma_f32 v2, -v146, v81, v2
	v_cndmask_b32_e32 v2, v230, v2, vcc
	v_add_f32_e32 v81, 0xc4000000, v18
	v_cmp_le_f32_e32 vcc, 0, v18
	v_fma_f32 v3, -v146, v81, v3
	s_nop 0
	v_cndmask_b32_e32 v18, v230, v19, vcc
	v_cmp_le_f32_e32 vcc, 0, v81
	v_add_f32_e32 v19, 0xc2000000, v80
	v_add_f32_e32 v81, 0xc4000000, v19
	v_cndmask_b32_e32 v3, v230, v3, vcc
	v_fma_f32 v20, -v146, v19, v20
	v_cmp_le_f32_e32 vcc, 0, v19
	v_fma_f32 v4, -v146, v81, v4
	s_nop 0
	v_cndmask_b32_e32 v19, v230, v20, vcc
	v_cmp_le_f32_e32 vcc, 0, v81
	v_add_f32_e32 v20, 0xc2400000, v80
	v_add_f32_e32 v81, 0xc4000000, v20
	v_cndmask_b32_e32 v4, v230, v4, vcc
	v_fma_f32 v21, -v146, v20, v21
	v_cmp_le_f32_e32 vcc, 0, v20
	v_fma_f32 v5, -v146, v81, v5
	s_nop 0
	v_cndmask_b32_e32 v20, v230, v21, vcc
	v_cmp_le_f32_e32 vcc, 0, v81
	v_add_f32_e32 v21, 0xc3000000, v80
	v_add_f32_e32 v81, 0xc4000000, v21
	v_cndmask_b32_e32 v5, v230, v5, vcc
	v_fma_f32 v22, -v146, v21, v22
	v_cmp_le_f32_e32 vcc, 0, v21
	v_fma_f32 v6, -v146, v81, v6
	s_nop 0
	v_cndmask_b32_e32 v21, v230, v22, vcc
	v_cmp_le_f32_e32 vcc, 0, v81
	v_add_f32_e32 v22, 0xc3100000, v80
	v_add_f32_e32 v81, 0xc4000000, v22
	v_cndmask_b32_e32 v6, v230, v6, vcc
	v_fma_f32 v23, -v146, v22, v23
	v_cmp_le_f32_e32 vcc, 0, v22
	v_fma_f32 v7, -v146, v81, v7
	s_nop 0
	v_cndmask_b32_e32 v22, v230, v23, vcc
	v_cmp_le_f32_e32 vcc, 0, v81
	v_add_f32_e32 v23, 0xc3200000, v80
	v_add_f32_e32 v81, 0xc4000000, v23
	v_cndmask_b32_e32 v7, v230, v7, vcc
	v_fma_f32 v24, -v146, v23, v24
	v_cmp_le_f32_e32 vcc, 0, v23
	v_fma_f32 v8, -v146, v81, v8
	s_nop 0
	v_cndmask_b32_e32 v23, v230, v24, vcc
	v_cmp_le_f32_e32 vcc, 0, v81
	v_add_f32_e32 v24, 0xc3300000, v80
	v_add_f32_e32 v81, 0xc4000000, v24
	v_cndmask_b32_e32 v8, v230, v8, vcc
	v_fma_f32 v25, -v146, v24, v25
	v_cmp_le_f32_e32 vcc, 0, v24
	v_fma_f32 v9, -v146, v81, v9
	s_nop 0
	v_cndmask_b32_e32 v24, v230, v25, vcc
	v_cmp_le_f32_e32 vcc, 0, v81
	v_add_f32_e32 v25, 0xc3800000, v80
	v_add_f32_e32 v81, 0xc4000000, v25
	v_cndmask_b32_e32 v9, v230, v9, vcc
	v_fma_f32 v26, -v146, v25, v26
	v_cmp_le_f32_e32 vcc, 0, v25
	v_fma_f32 v10, -v146, v81, v10
	s_nop 0
	v_cndmask_b32_e32 v25, v230, v26, vcc
	v_cmp_le_f32_e32 vcc, 0, v81
	v_add_f32_e32 v26, 0xc3880000, v80
	v_add_f32_e32 v81, 0xc4000000, v26
	v_cndmask_b32_e32 v10, v230, v10, vcc
	v_fma_f32 v27, -v146, v26, v27
	v_cmp_le_f32_e32 vcc, 0, v26
	v_fma_f32 v11, -v146, v81, v11
	s_nop 0
	v_cndmask_b32_e32 v26, v230, v27, vcc
	v_cmp_le_f32_e32 vcc, 0, v81
	v_add_f32_e32 v27, 0xc3900000, v80
	v_add_f32_e32 v81, 0xc4000000, v27
	v_cndmask_b32_e32 v11, v230, v11, vcc
	v_fma_f32 v28, -v146, v27, v28
	v_cmp_le_f32_e32 vcc, 0, v27
	v_fma_f32 v12, -v146, v81, v12
	s_nop 0
	v_cndmask_b32_e32 v27, v230, v28, vcc
	v_cmp_le_f32_e32 vcc, 0, v81
	v_add_f32_e32 v28, 0xc3980000, v80
; DI float fexp2(float x) { return __builtin_amdgcn_exp2f(x); }
; template <int MODE> DI void attn_h1(AttnCtx& c, const bf16x8 (&q)[8], f32x16 (&o)[4], f32x16& s0, f32x16& s1, ldsp lds, int kbuf, int bbuf, int tj, int lane) {
;     ...
;             if (MODE != MD_CMP2) {
;                 float mx = s0[0];
; #pragma unroll
;                 for (int e = 1; e < 16; ++e) mx = fmaxf(mx, s0[e]);
; #pragma unroll
;                 for (int e = 0; e < 16; ++e) mx = fmaxf(mx, s1[e]);
;                 { typedef unsigned u2_t __attribute__((ext_vector_type(2)));
;                   const unsigned mb = __builtin_bit_cast(unsigned, mx);
;                   const u2_t sw = __builtin_amdgcn_permlane32_swap(mb, mb, false, false);
;                   mx = fmaxf(__builtin_bit_cast(float, sw.x), __builtin_bit_cast(float, sw.y)); }
;                 const bool need = mx > c.m + 12.0f;
;                 if (__ballot(need) != 0ull) {
;                     const float mnew = need ? mx : c.m;
;                     const float alpha = fexp2(c.m - ((mnew == NINF) ? 0.f : mnew));
;                     c.l *= alpha; c.m = mnew;
;                     if (MODE != MD_CMP1) {
; #pragma unroll
;                         for (int db = 0; db < 4; ++db)
; #pragma unroll
;                             for (int e = 0; e < 16; ++e) o[db][e] *= alpha;
;                     }
;                 }
; template <int MODE> DI void attn_h2(AttnCtx& c, f32x16 (&o)[4], f32x16& s0, f32x16& s1, ldsp lds, int vbuf, int tj, int lane) {
;     ...
;             } else {
;                 const float muse = (c.m == NINF) ? 0.f : c.m;
;                 float ps = 0.f;
; #pragma unroll
;                 for (int e = 0; e < 16; ++e) { s0[e] = fexp2(s0[e] - muse); s1[e] = fexp2(s1[e] - muse); ps += s0[e] + s1[e]; }
;                 c.l += ps;
	v_add_f32_e32 v81, 0xc4000000, v28
	v_cndmask_b32_e32 v12, v230, v12, vcc
	v_fma_f32 v29, -v146, v28, v29
	v_cmp_le_f32_e32 vcc, 0, v28
	v_fma_f32 v13, -v146, v81, v13
	s_nop 0
	v_cndmask_b32_e32 v28, v230, v29, vcc
	v_cmp_le_f32_e32 vcc, 0, v81
	v_add_f32_e32 v29, 0xc3c00000, v80
	v_add_f32_e32 v81, 0xc4000000, v29
	v_cndmask_b32_e32 v13, v230, v13, vcc
	v_fma_f32 v30, -v146, v29, v30
	v_cmp_le_f32_e32 vcc, 0, v29
	v_fma_f32 v14, -v146, v81, v14
	s_nop 0
	v_cndmask_b32_e32 v29, v230, v30, vcc
	v_cmp_le_f32_e32 vcc, 0, v81
	v_add_f32_e32 v30, 0xc3c80000, v80
	v_add_f32_e32 v81, 0xc4000000, v30
	v_cndmask_b32_e32 v14, v230, v14, vcc
	v_fma_f32 v31, -v146, v30, v31
	v_cmp_le_f32_e32 vcc, 0, v30
	v_fma_f32 v15, -v146, v81, v15
	s_nop 0
	v_cndmask_b32_e32 v30, v230, v31, vcc
	v_cmp_le_f32_e32 vcc, 0, v81
	v_add_f32_e32 v31, 0xc3d00000, v80
	v_add_f32_e32 v81, 0xc4000000, v31
	v_cndmask_b32_e32 v15, v230, v15, vcc
	v_fma_f32 v32, -v146, v31, v32
	v_cmp_le_f32_e32 vcc, 0, v31
	v_fma_f32 v16, -v146, v81, v16
	s_nop 0
	v_cndmask_b32_e32 v31, v230, v32, vcc
	v_cmp_le_f32_e32 vcc, 0, v81
	v_add_f32_e32 v32, 0xc3d80000, v80
	v_fma_f32 v33, -v146, v32, v33
	v_cndmask_b32_e32 v16, v230, v16, vcc
	v_cmp_le_f32_e32 vcc, 0, v32
	v_add_f32_e32 v80, 0xc4000000, v32
	v_fma_f32 v17, -v146, v80, v17
	v_cndmask_b32_e32 v32, v230, v33, vcc
	v_max_f32_e32 v33, v0, v18
	v_max3_f32 v33, v33, v19, v20
	v_max3_f32 v33, v33, v21, v22
	v_max3_f32 v33, v33, v23, v24
	v_max3_f32 v33, v33, v25, v26
	v_max3_f32 v33, v33, v27, v28
	v_max3_f32 v33, v33, v29, v30
	v_max3_f32 v33, v33, v31, v32
	v_max3_f32 v33, v33, v2, v3
	v_max3_f32 v33, v33, v4, v5
	v_max3_f32 v33, v33, v6, v7
	v_max3_f32 v33, v33, v8, v9
	v_max3_f32 v33, v33, v10, v11
	v_cmp_le_f32_e32 vcc, 0, v80
	v_max3_f32 v33, v33, v12, v13
	v_max3_f32 v33, v33, v14, v15
	v_cndmask_b32_e32 v17, v230, v17, vcc
	v_max3_f32 v33, v33, v16, v17
	v_mov_b32_e32 v80, v33
	s_nop 1
	v_permlane32_swap_b32_e32 v33, v80
	v_add_f32_e32 v80, 0x41400000, v155
	v_cmp_lt_f32_e32 vcc, v80, v33
	s_cmp_eq_u64 vcc, 0
	s_nop 0
	v_cndmask_b32_e32 v33, v155, v33, vcc
	v_cmp_neq_f32_e32 vcc, s29, v33
	s_nop 1
	v_cndmask_b32_e32 v80, 0, v33, vcc
	s_cselect_b64 vcc, -1, 0
	v_sub_f32_e32 v80, v155, v80
	v_cndmask_b32_e32 v155, v33, v155, vcc
	v_cmp_neq_f32_e64 s[46:47], s29, v155
	s_nop 1
	v_cndmask_b32_e64 v33, 0, v155, s[46:47]
	v_sub_f32_e32 v0, v0, v33
	v_exp_f32_e32 v81, v0
	v_sub_f32_e32 v0, v2, v33
	v_exp_f32_e32 v82, v0
	v_sub_f32_e32 v0, v18, v33
	v_exp_f32_e32 v2, v0
	v_sub_f32_e32 v0, v3, v33
	v_exp_f32_e32 v0, v0
	v_add_f32_e32 v3, v81, v82
	v_add_f32_e64 v2, v2, v0
	v_add_f32_e64 v3, v3, v1
	s_nop 0
	v_add_f32_e64 v3, v2, v3
	v_add_f32_e64 v2, v2, v2
	v_sub_f32_e32 v2, v4, v33
	v_sub_f32_e32 v0, v19, v33
	v_exp_f32_e32 v18, v2
	v_sub_f32_e32 v2, v20, v33
	v_exp_f32_e32 v0, v0
	v_exp_f32_e32 v4, v2
	v_sub_f32_e32 v2, v5, v33
	v_exp_f32_e32 v2, v2
	v_add_f32_e32 v5, v0, v18
	v_sub_f32_e32 v0, v21, v33
	v_exp_f32_e32 v0, v0
	v_add_f32_e64 v2, v4, v2
	v_add_f32_e64 v3, v5, v3
	s_nop 0
	v_add_f32_e64 v3, v2, v3
	v_add_f32_e64 v2, v2, v2
	v_sub_f32_e32 v2, v6, v33
	v_exp_f32_e32 v5, v2
	v_sub_f32_e32 v2, v22, v33
	v_exp_f32_e32 v4, v2
	v_sub_f32_e32 v2, v7, v33
	v_exp_f32_e32 v2, v2
	v_add_f32_e32 v5, v0, v5
	v_sub_f32_e32 v0, v23, v33
	v_exp_f32_e32 v0, v0
	v_add_f32_e64 v2, v4, v2
	v_add_f32_e64 v3, v5, v3
	v_exp_f32_e32 v6, v80
	v_add_f32_e64 v3, v2, v3
	v_add_f32_e64 v2, v2, v2
	v_sub_f32_e32 v2, v8, v33
	v_exp_f32_e32 v5, v2
	v_sub_f32_e32 v2, v24, v33
	v_exp_f32_e32 v4, v2
	v_sub_f32_e32 v2, v9, v33
	v_exp_f32_e32 v2, v2
	v_add_f32_e32 v5, v0, v5
	v_sub_f32_e32 v0, v25, v33
	v_exp_f32_e32 v0, v0
	v_add_f32_e64 v2, v4, v2
	v_add_f32_e64 v3, v5, v3
	v_mul_f32_e32 v6, v62, v6
	v_add_f32_e64 v3, v2, v3
	v_add_f32_e64 v2, v2, v2
	v_sub_f32_e32 v2, v10, v33
	v_exp_f32_e32 v5, v2
	v_sub_f32_e32 v2, v26, v33
	v_exp_f32_e32 v4, v2
	v_sub_f32_e32 v2, v11, v33
	v_exp_f32_e32 v2, v2
	v_add_f32_e32 v5, v0, v5
	v_sub_f32_e32 v0, v27, v33
	v_exp_f32_e32 v0, v0
	v_add_f32_e64 v2, v4, v2
	v_add_f32_e64 v3, v5, v3
	v_cndmask_b32_e32 v6, v6, v62, vcc
	v_add_f32_e64 v3, v2, v3
	v_add_f32_e64 v2, v2, v2
	v_sub_f32_e32 v2, v12, v33
	v_exp_f32_e32 v5, v2
	v_sub_f32_e32 v2, v28, v33
	v_exp_f32_e32 v4, v2
	v_sub_f32_e32 v2, v13, v33
	v_exp_f32_e32 v2, v2
	v_add_f32_e32 v5, v0, v5
	v_sub_f32_e32 v0, v29, v33
	v_exp_f32_e32 v0, v0
	v_add_f32_e64 v2, v4, v2
	v_add_f32_e64 v3, v5, v3
	s_nop 0
	v_add_f32_e64 v3, v2, v3
	v_add_f32_e64 v2, v2, v2
	v_sub_f32_e32 v2, v14, v33
	v_exp_f32_e32 v5, v2
	v_sub_f32_e32 v2, v30, v33
	v_exp_f32_e32 v4, v2
	v_sub_f32_e32 v2, v15, v33
	v_exp_f32_e32 v2, v2
	v_add_f32_e32 v5, v0, v5
	v_sub_f32_e32 v0, v31, v33
	v_exp_f32_e32 v0, v0
	v_add_f32_e64 v2, v4, v2
	v_add_f32_e64 v3, v5, v3
	s_nop 0
	v_add_f32_e64 v3, v2, v3
	v_add_f32_e64 v2, v2, v2
	v_sub_f32_e32 v2, v16, v33
	v_exp_f32_e32 v5, v2
	v_sub_f32_e32 v2, v32, v33
	v_exp_f32_e32 v4, v2
	v_sub_f32_e32 v2, v17, v33
	v_exp_f32_e32 v2, v2
	v_add_f32_e32 v5, v0, v5
	v_add_f32_e64 v2, v4, v2
	v_add_f32_e64 v3, v5, v3
	s_nop 0
	v_add_f32_e32 v0, v2, v3
	v_add_f32_e32 v62, v6, v0
	s_andn2_b64 vcc, exec, s[30:31]
	s_cbranch_vccnz .LBB0_612

; template <int MODE> DI void attn_run(AttnCtx& c, const bf16x8 (&q)[8], f32x16 (&o)[4], ldsp lds, int tid, int wv) {
;     ...
;         if (MODE == MD_FOX || ((MODE == MD_SEL || MODE == MD_CMP1 || MODE == MD_CMP2) && c.xsel)) {
;             const bool needs = (cb_next + c.bqk >= c.m - 32.0f);
;             const unsigned wn = (__ballot(needs) != 0ull) ? 1u : 0u;
;             wneed = (wn != 0u);
;             if (lane == 0) xflag[(i & 1) * NWAVES + wv] = wn;
;         }
.LBB0_616:
	v_add_f32_e64 v2, v154, v190
	v_add_f32_e64 v3, v155, v191
	s_nop 0
	v_cmp_ge_f32_e32 vcc, v2, v3
	s_cmp_lg_u64 vcc, 0
	s_cselect_b64 s[34:35], -1, 0
	s_and_saveexec_b64 s[30:31], s[40:41]
	s_cbranch_execz .LBB0_603
	s_lshl_b32 s28, s28, 5
	v_readlane_b32 s29, v254, 49
	s_add_i32 s28, s29, s28
	v_cndmask_b32_e64 v0, 0, 1, s[34:35]
	v_mov_b32_e32 v2, s28
	ds_write_b32 v2, v0
	s_branch .LBB0_603

; template <int MODE> DI void attn_h1(AttnCtx& c, const bf16x8 (&q)[8], f32x16 (&o)[4], f32x16& s0, f32x16& s1, ldsp lds, int kbuf, int bbuf, int tj, int lane) {
;     ...
;                 } else {
;                     const float a0 = selbit ? -c.slope2 * dbase : NINF;
; #pragma unroll
;                     for (int e = 0; e < 16; ++e) {
;                         s0[e] = fmaf(c.slope2, (float)(PS * (8 * (e >> 2) + (e & 3))), s0[e] + a0);
;                         s1[e] = fmaf(c.slope2, (float)(PS * (32 + 8 * (e >> 2) + (e & 3))), s1[e] + a0);
;                     }
;                 }
.LBB0_913:
	s_andn2_b64 vcc, exec, s[4:5]
	s_cbranch_vccnz .LBB0_915
	v_mul_f32_e64 v0, -v146, v217
	v_cndmask_b32_e64 v218, v230, v0, s[2:3]
	s_mov_b32 s2, 0x42000000
	v_add_f32_e64 v2, v2, v218
	v_add_f32_e64 v3, v3, v218
	s_mov_b32 s3, 0x42040000
	v_fma_f32 v184, v146, s2, v2
	v_fma_f32 v185, v147, s3, v3
	s_mov_b32 s2, 2.0
	v_add_f32_e64 v2, v84, v218
	v_add_f32_e64 v3, v85, v218
	s_mov_b32 s3, 0x40400000
	v_fma_f32 v180, v146, s2, v2
	v_fma_f32 v181, v147, s3, v3
	s_mov_b32 s2, 0x42080000
	v_add_f32_e64 v2, v4, v218
	v_add_f32_e64 v3, v5, v218
	s_mov_b32 s3, 0x420c0000
	v_fma_f32 v186, v146, s2, v2
	v_fma_f32 v187, v147, s3, v3
	s_mov_b32 s2, 0x41000000
	v_add_f32_e64 v2, v86, v218
	v_add_f32_e64 v3, v87, v218
	s_mov_b32 s3, 0x41100000
	v_fma_f32 v182, v146, s2, v2
	v_fma_f32 v183, v147, s3, v3
	s_mov_b32 s2, 0x42200000
	v_add_f32_e64 v2, v6, v218
	v_add_f32_e64 v3, v7, v218
	s_mov_b32 s3, 0x42240000
	v_fma_f32 v172, v146, s2, v2
	v_fma_f32 v173, v147, s3, v3
	s_mov_b32 s2, 0x41200000
	v_add_f32_e64 v2, v88, v218
	v_add_f32_e64 v3, v89, v218
	s_mov_b32 s3, 0x41300000
	v_fma_f32 v178, v146, s2, v2
	v_fma_f32 v179, v147, s3, v3
	s_mov_b32 s2, 0x42280000
	v_add_f32_e64 v2, v8, v218
	v_add_f32_e64 v3, v9, v218
	s_mov_b32 s3, 0x422c0000
	v_fma_f32 v164, v146, s2, v2
	v_fma_f32 v165, v147, s3, v3
	s_mov_b32 s2, 0x41800000
	v_add_f32_e64 v2, v90, v218
	v_add_f32_e64 v3, v91, v218
	s_mov_b32 s3, 0x41880000
	v_fma_f32 v168, v146, s2, v2
	v_fma_f32 v169, v147, s3, v3
	s_mov_b32 s2, 0x42400000
	v_add_f32_e64 v2, v10, v218
	v_add_f32_e64 v3, v11, v218
	s_mov_b32 s3, 0x42440000
	v_fma_f32 v166, v146, s2, v2
	v_fma_f32 v167, v147, s3, v3
	s_mov_b32 s2, 0x41900000
	v_add_f32_e64 v2, v92, v218
	v_add_f32_e64 v3, v93, v218
	s_mov_b32 s3, 0x41980000
	v_fma_f32 v170, v146, s2, v2
	v_fma_f32 v171, v147, s3, v3
	s_mov_b32 s2, 0x42480000
	v_add_f32_e64 v2, v12, v218
	v_add_f32_e64 v3, v13, v218
	s_mov_b32 s3, 0x424c0000
	v_fma_f32 v160, v146, s2, v2
	v_fma_f32 v161, v147, s3, v3
	s_mov_b32 s2, 0x41c00000
	v_add_f32_e64 v2, v94, v218
	v_add_f32_e64 v3, v95, v218
	s_mov_b32 s3, 0x41c80000
	v_fma_f32 v174, v146, s2, v2
	v_fma_f32 v175, v147, s3, v3
	s_mov_b32 s2, 0x42600000
	v_add_f32_e64 v2, v14, v218
	v_add_f32_e64 v3, v15, v218
	s_mov_b32 s3, 0x42640000
	v_fma_f32 v162, v146, s2, v2
	v_fma_f32 v163, v147, s3, v3
	s_mov_b32 s2, 0x41d00000
	v_add_f32_e32 v0, v82, v218
	v_add_f32_e32 v82, v83, v218
	v_add_f32_e32 v214, v16, v218
	v_add_f32_e64 v2, v96, v218
	v_add_f32_e64 v3, v97, v218
	s_mov_b32 s3, 0x41d80000
	v_add_f32_e32 v215, v17, v218
	v_fmac_f32_e32 v0, 0, v146
	v_add_f32_e32 v216, v146, v82
	v_fmac_f32_e32 v214, 0x42680000, v146
	v_fma_f32 v176, v146, s2, v2
	v_fma_f32 v177, v147, s3, v3
	v_fmac_f32_e32 v215, 0x426c0000, v146

; #define LAS __attribute__((address_space(3)))
; DI unsigned pk2(float lo, float hi) { f32x2_t v = {lo, hi}; bf16x2_t b = __builtin_convertvector(v, bf16x2_t); return __builtin_bit_cast(unsigned, b); }
; DI float fexp2(float x) { return __builtin_amdgcn_exp2f(x); }
; #define MFMA32(a, b, c) __builtin_amdgcn_mfma_f32_32x32x16_bf16((a), (b), (c), 0, 0, 0)
; template <int MODE> DI void attn_h2(AttnCtx& c, f32x16 (&o)[4], f32x16& s0, f32x16& s1, ldsp lds, int vbuf, int tj, int lane) {
;     ...
;             } else {
;                 const float muse = (c.m == NINF) ? 0.f : c.m;
;                 float ps = 0.f;
; #pragma unroll
;                 for (int e = 0; e < 16; ++e) { s0[e] = fexp2(s0[e] - muse); s1[e] = fexp2(s1[e] - muse); ps += s0[e] + s1[e]; }
;                 c.l += ps;
;                         }
;             if (MODE != MD_CMP1) {
;                 ldsp vl = lds + vbuf + r32 * VPITCH + 16 * h;
; #pragma unroll
;                 for (int kb = 0; kb < 2; ++kb)
; #pragma unroll
;                     for (int s2 = 0; s2 < 2; ++s2) {
;                         u32x4 pw;
;                         if (kb == 0) { pw.x = pk2(s0[8 * s2], s0[8 * s2 + 1]); pw.y = pk2(s0[8 * s2 + 2], s0[8 * s2 + 3]); pw.z = pk2(s0[8 * s2 + 4], s0[8 * s2 + 5]); pw.w = pk2(s0[8 * s2 + 6], s0[8 * s2 + 7]); }
;                         else { pw.x = pk2(s1[8 * s2], s1[8 * s2 + 1]); pw.y = pk2(s1[8 * s2 + 2], s1[8 * s2 + 3]); pw.z = pk2(s1[8 * s2 + 4], s1[8 * s2 + 5]); pw.w = pk2(s1[8 * s2 + 6], s1[8 * s2 + 7]); }
;                         const bf16x8 pf = __builtin_bit_cast(bf16x8, pw);
; #pragma unroll
;                         for (int db = 0; db < 4; ++db) {
;                             const bf16x8 vf = *(const LAS bf16x8*)(vl + db * 32 * VPITCH + (kb * 2 + s2) * 32);
;                             o[db] = MFMA32(vf, pf, o[db]);
;                         }
;                     }
;             }
.LBB0_917:
	v_cmp_neq_f32_e32 vcc, s53, v155
	s_mul_i32 s2, s20, 0x4800
	v_add_u32_e32 v15, s2, v213
	v_cndmask_b32_e32 v14, 0, v155, vcc
	v_sub_f32_e32 v0, v0, v14
	v_exp_f32_e32 v7, v0
	v_sub_f32_e32 v0, v184, v14
	v_exp_f32_e32 v13, v0
	v_sub_f32_e32 v0, v216, v14
	v_exp_f32_e32 v8, v0
	v_sub_f32_e32 v0, v185, v14
	v_exp_f32_e32 v0, v0
	v_add_f32_e32 v9, v7, v13
	ds_read_b128 v[82:85], v15 offset:34816
	v_cvt_pk_bf16_f32 v86, v7, v8
	v_add_f32_e64 v2, v8, v0
	v_add_f32_e64 v3, v9, v1
	v_sub_f32_e32 v7, v168, v14
	v_add_f32_e64 v3, v2, v3
	v_add_f32_e64 v2, v2, v2
	v_sub_f32_e32 v2, v180, v14
	v_exp_f32_e32 v12, v2
	v_sub_f32_e32 v2, v186, v14
	v_exp_f32_e32 v9, v2
	v_sub_f32_e32 v2, v181, v14
	v_exp_f32_e32 v10, v2
	v_sub_f32_e32 v2, v187, v14
	v_exp_f32_e32 v2, v2
	v_add_f32_e32 v11, v12, v9
	ds_read_b128 v[90:93], v15 offset:34848
	ds_read_b128 v[94:97], v15 offset:39424
	v_cvt_pk_bf16_f32 v87, v12, v10
	v_add_f32_e64 v4, v10, v2
	v_add_f32_e64 v5, v11, v3
	v_sub_f32_e32 v3, v182, v14
	v_add_f32_e64 v5, v4, v5
	v_add_f32_e64 v4, v4, v4
	v_sub_f32_e32 v4, v183, v14
	v_exp_f32_e32 v6, v4
	v_sub_f32_e32 v4, v178, v14
	v_exp_f32_e32 v11, v4
	v_sub_f32_e32 v4, v179, v14
	v_exp_f32_e32 v16, v4
	v_sub_f32_e32 v4, v172, v14
	v_exp_f32_e32 v3, v3
	v_exp_f32_e32 v182, v4
	v_sub_f32_e32 v4, v173, v14
	v_exp_f32_e32 v173, v7
	v_sub_f32_e32 v7, v169, v14
	v_exp_f32_e32 v172, v7
	v_sub_f32_e32 v7, v170, v14
	v_exp_f32_e32 v183, v7
	v_sub_f32_e32 v7, v171, v14
	v_exp_f32_e32 v12, v7
	v_sub_f32_e32 v7, v174, v14
	v_cvt_pk_bf16_f32 v88, v3, v6
	v_cvt_pk_bf16_f32 v89, v11, v16
	v_exp_f32_e32 v174, v7
	v_sub_f32_e32 v7, v175, v14
	v_exp_f32_e32 v4, v4
	s_waitcnt lgkmcnt(2)
	v_mfma_f32_32x32x16_bf16 v[66:81], v[82:85], v[86:89], v[66:81]
	ds_read_b128 v[82:85], v15 offset:44032
	ds_read_b128 v[178:181], v15 offset:39456
	v_exp_f32_e32 v10, v7
	v_sub_f32_e32 v7, v176, v14
	v_exp_f32_e32 v175, v7
	v_sub_f32_e32 v7, v177, v14
	v_exp_f32_e32 v8, v7
	v_add_f32_e32 v7, v3, v182
	s_waitcnt lgkmcnt(2)
	v_mfma_f32_32x32x16_bf16 v[50:65], v[94:97], v[86:89], v[50:65]
	ds_read_b128 v[94:97], v15 offset:48640
	ds_read_b128 v[168:171], v15 offset:44064
	v_add_f32_e64 v6, v6, v4
	v_add_f32_e64 v7, v7, v5
	v_sub_f32_e32 v3, v164, v14
	v_exp_f32_e32 v3, v3
	v_sub_f32_e32 v5, v165, v14
	v_add_f32_e32 v17, v11, v3
	s_waitcnt lgkmcnt(1)
	v_mfma_f32_32x32x16_bf16 v[18:33], v[94:97], v[86:89], v[18:33]
	v_add_f32_e64 v94, v6, v6
	v_add_f32_e64 v95, v6, v7
	v_exp_f32_e32 v94, v5
	v_sub_f32_e32 v5, v166, v14
	v_exp_f32_e32 v164, v5
	v_sub_f32_e32 v5, v167, v14
	v_add_f32_e64 v6, v16, v94
	v_add_f32_e64 v7, v17, v95
	v_mfma_f32_32x32x16_bf16 v[34:49], v[82:85], v[86:89], v[34:49]
	ds_read_b128 v[82:85], v15 offset:48672
	v_cvt_pk_bf16_f32 v86, v173, v172
	v_cvt_pk_bf16_f32 v87, v183, v12
	v_cvt_pk_bf16_f32 v88, v174, v10
	v_cvt_pk_bf16_f32 v89, v175, v8
	v_add_f32_e64 v7, v6, v7
	v_add_f32_e64 v6, v6, v6
	v_exp_f32_e32 v6, v5
	v_mfma_f32_32x32x16_bf16 v[66:81], v[90:93], v[86:89], v[66:81]
	ds_read_b128 v[90:93], v15 offset:34880
	v_add_f32_e32 v173, v173, v164
	v_add_f32_e64 v16, v172, v6
	v_add_f32_e64 v17, v173, v7
	v_sub_f32_e32 v7, v161, v14
	v_add_f32_e64 v17, v16, v17
	v_add_f32_e64 v16, v16, v16
	v_exp_f32_e32 v16, v7
	v_mfma_f32_32x32x16_bf16 v[50:65], v[178:181], v[86:89], v[50:65]
	s_waitcnt lgkmcnt(2)
	v_mfma_f32_32x32x16_bf16 v[34:49], v[168:171], v[86:89], v[34:49]
	s_waitcnt lgkmcnt(1)
	v_mfma_f32_32x32x16_bf16 v[18:33], v[82:85], v[86:89], v[18:33]
	v_cvt_pk_bf16_f32 v82, v13, v0
	v_sub_f32_e32 v0, v160, v14
	v_exp_f32_e32 v0, v0
	v_cvt_pk_bf16_f32 v83, v9, v2
	v_cvt_pk_bf16_f32 v84, v182, v4
	v_cvt_pk_bf16_f32 v85, v3, v94
	ds_read_b128 v[2:5], v15 offset:39488
	ds_read_b128 v[86:89], v15 offset:34912
	s_waitcnt lgkmcnt(2)
	v_mfma_f32_32x32x16_bf16 v[66:81], v[90:93], v[82:85], v[66:81]
	ds_read_b128 v[90:93], v15 offset:44096
	ds_read_b128 v[94:97], v15 offset:39520
	v_add_f32_e32 v13, v183, v0
	v_sub_f32_e32 v9, v163, v14
	s_waitcnt lgkmcnt(3)
	v_mfma_f32_32x32x16_bf16 v[50:65], v[2:5], v[82:85], v[50:65]
	v_add_f32_e64 v2, v12, v16
	v_add_f32_e64 v3, v13, v17
	v_add_f32_e64 v160, v2, v2
	v_add_f32_e64 v161, v2, v3
	v_sub_f32_e32 v2, v162, v14
	v_exp_f32_e32 v7, v2
	ds_read_b128 v[2:5], v15 offset:44128
	v_exp_f32_e32 v160, v9
	s_waitcnt lgkmcnt(2)
	v_mfma_f32_32x32x16_bf16 v[34:49], v[90:93], v[82:85], v[34:49]
	ds_read_b128 v[90:93], v15 offset:48704
	v_add_f32_e32 v11, v174, v7
	v_add_f32_e64 v10, v10, v160
	v_add_f32_e64 v11, v11, v161
	v_sub_f32_e32 v9, v214, v14
	v_add_f32_e64 v162, v10, v10
	v_add_f32_e64 v163, v10, v11
	ds_read_b128 v[10:13], v15 offset:48736
	v_sub_f32_e32 v14, v215, v14
	s_waitcnt lgkmcnt(1)
	v_mfma_f32_32x32x16_bf16 v[18:33], v[90:93], v[82:85], v[18:33]
	v_exp_f32_e32 v9, v9
	v_exp_f32_e32 v162, v14
	v_cvt_pk_bf16_f32 v14, v164, v6
	v_cvt_pk_bf16_f32 v15, v0, v16
	v_cvt_pk_bf16_f32 v16, v7, v160
	v_cvt_pk_bf16_f32 v17, v9, v162
	v_add_f32_e32 v9, v175, v9
	s_nop 0
	v_mfma_f32_32x32x16_bf16 v[66:81], v[86:89], v[14:17], v[66:81]
	v_mfma_f32_32x32x16_bf16 v[50:65], v[94:97], v[14:17], v[50:65]
	v_mfma_f32_32x32x16_bf16 v[34:49], v[2:5], v[14:17], v[34:49]
	v_add_f32_e64 v2, v8, v162
	v_add_f32_e64 v3, v9, v163
	v_add_f32_e32 v0, v2, v3
	v_add_f32_e32 v210, v210, v0
	s_waitcnt lgkmcnt(0)
	v_mfma_f32_32x32x16_bf16 v[18:33], v[10:13], v[14:17], v[18:33]

; template <int MODE> DI void attn_run(AttnCtx& c, const bf16x8 (&q)[8], f32x16 (&o)[4], ldsp lds, int tid, int wv) {
;     ...
;         if (MODE == MD_FOX || ((MODE == MD_SEL || MODE == MD_CMP1 || MODE == MD_CMP2) && c.xsel)) {
;             const bool needs = (cb_next + c.bqk >= c.m - 32.0f);
;             const unsigned wn = (__ballot(needs) != 0ull) ? 1u : 0u;
;             wneed = (wn != 0u);
;             if (lane == 0) xflag[(i & 1) * NWAVES + wv] = wn;
;         }
.LBB0_920:
	s_and_b64 vcc, exec, s[42:43]
	s_cbranch_vccnz .LBB0_924
	v_add_f32_e64 v2, v154, v190
	v_add_f32_e64 v3, v155, v191
	s_nop 0
	v_cmp_ge_f32_e32 vcc, v2, v3
	s_cmp_lg_u64 vcc, 0
	s_cselect_b64 s[6:7], -1, 0
	s_and_saveexec_b64 s[2:3], s[40:41]
	s_lshl_b32 s4, s38, 5
	s_add_i32 s4, s28, s4
	v_cndmask_b32_e64 v0, 0, 1, s[6:7]
	v_mov_b32_e32 v2, s4
	ds_write_b32 v2, v0
	s_or_b64 exec, exec, s[2:3]

; #define LAS __attribute__((address_space(3)))
; #define MFMA32(a, b, c) __builtin_amdgcn_mfma_f32_32x32x16_bf16((a), (b), (c), 0, 0, 0)
; template <int MODE> DI void attn_h1(AttnCtx& c, const bf16x8 (&q)[8], f32x16 (&o)[4], f32x16& s0, f32x16& s1, ldsp lds, int kbuf, int bbuf, int tj, int lane) {
;     const int r32 = lane & 31, h = lane >> 5;
;             ldsp kl = lds + kbuf + r32 * KPITCH + h * 16;
; #pragma unroll
;             for (int e = 0; e < 16; ++e) { s0[e] = 0.f; s1[e] = 0.f; }
; #pragma unroll
;             for (int s = 0; s < 8; ++s) {
;                 const bf16x8 ka = *(const LAS bf16x8*)(kl + s * 32), kb = *(const LAS bf16x8*)(kl + 32 * KPITCH + s * 32);
;                 s0 = MFMA32(ka, q[s], s0); s1 = MFMA32(kb, q[s], s1);
;                 if (s == 3) asm volatile("" ::: "memory");
;             }
;     ...
;                 } else {
;                     const float a0 = selbit ? -c.slope2 * dbase : NINF;
; #pragma unroll
;                     for (int e = 0; e < 16; ++e) {
;                         s0[e] = fmaf(c.slope2, (float)(PS * (8 * (e >> 2) + (e & 3))), s0[e] + a0);
;                         s1[e] = fmaf(c.slope2, (float)(PS * (32 + 8 * (e >> 2) + (e & 3))), s1[e] + a0);
;                     }
;                 }
.LBB0_1066:
	s_and_b32 s19, s18, 1
	s_mul_i32 s2, s19, 0x4400
	v_add_u32_e32 v148, s2, v0
	ds_read_b128 v[66:69], v148 offset:8704
	ds_read_b128 v[70:73], v148
	ds_read_b128 v[160:163], v148 offset:32
	ds_read_b128 v[164:167], v148 offset:8736
	v_cvt_f32_i32_e32 v176, v198
	s_mov_b64 s[2:3], -1
	s_waitcnt lgkmcnt(2)
	v_mfma_f32_32x32x16_bf16 v[82:97], v[70:73], v[98:101], 0
	s_cmp_lg_u32 s18, 8
	v_mfma_f32_32x32x16_bf16 v[66:81], v[66:69], v[98:101], 0
	s_waitcnt lgkmcnt(1)
	v_mfma_f32_32x32x16_bf16 v[82:97], v[160:163], v[102:105], v[82:97]
	s_waitcnt lgkmcnt(0)
	v_mfma_f32_32x32x16_bf16 v[66:81], v[164:167], v[102:105], v[66:81]
	ds_read_b128 v[160:163], v148 offset:8768
	ds_read_b128 v[164:167], v148 offset:64
	s_waitcnt lgkmcnt(0)
	v_mfma_f32_32x32x16_bf16 v[82:97], v[164:167], v[106:109], v[82:97]
	v_mfma_f32_32x32x16_bf16 v[66:81], v[160:163], v[106:109], v[66:81]
	ds_read_b128 v[160:163], v148 offset:8800
	ds_read_b128 v[164:167], v148 offset:96
	s_waitcnt lgkmcnt(0)
	v_mfma_f32_32x32x16_bf16 v[82:97], v[164:167], v[110:113], v[82:97]
	v_mfma_f32_32x32x16_bf16 v[66:81], v[160:163], v[110:113], v[66:81]
	ds_read_b128 v[160:163], v148 offset:8832
	ds_read_b128 v[164:167], v148 offset:128
	ds_read_b128 v[168:171], v148 offset:160
	s_waitcnt lgkmcnt(1)
	v_mfma_f32_32x32x16_bf16 v[82:97], v[164:167], v[114:117], v[82:97]
	v_mfma_f32_32x32x16_bf16 v[66:81], v[160:163], v[114:117], v[66:81]
	ds_read_b128 v[160:163], v148 offset:8864
	s_waitcnt lgkmcnt(1)
	v_mfma_f32_32x32x16_bf16 v[82:97], v[168:171], v[118:121], v[82:97]
	s_waitcnt lgkmcnt(0)
	v_mfma_f32_32x32x16_bf16 v[66:81], v[160:163], v[118:121], v[66:81]
	ds_read_b128 v[160:163], v148 offset:8896
	ds_read_b128 v[164:167], v148 offset:192
	s_waitcnt lgkmcnt(0)
	v_mfma_f32_32x32x16_bf16 v[82:97], v[164:167], v[122:125], v[82:97]
	v_mfma_f32_32x32x16_bf16 v[66:81], v[160:163], v[122:125], v[66:81]
	ds_read_b128 v[160:163], v148 offset:8928
	ds_read_b128 v[164:167], v148 offset:224
	s_waitcnt lgkmcnt(0)
	v_mfma_f32_32x32x16_bf16 v[82:97], v[164:167], v[126:129], v[82:97]
	v_mfma_f32_32x32x16_bf16 v[66:81], v[160:163], v[126:129], v[66:81]
	s_nop 10
	v_fma_f32 v201, -v146, v176, v82
	s_cbranch_scc0 .LBB0_1068
	v_mul_f32_e64 v184, -v146, v176
	v_fma_f32 v148, -v146, v176, v83
	s_mov_b32 s2, 0x42000000
	v_add_f32_e32 v177, v146, v148
	v_add_f32_e64 v148, v184, v66
	v_add_f32_e64 v149, v184, v67
	s_mov_b32 s3, 0x42040000
	v_fma_f32 v154, v146, s2, v148
	v_fma_f32 v155, v147, s3, v149
	s_mov_b32 s2, 2.0
	v_add_f32_e64 v148, v184, v84
	v_add_f32_e64 v149, v184, v85
	s_mov_b32 s3, 0x40400000
	v_fma_f32 v148, v146, s2, v148
	v_fma_f32 v149, v147, s3, v149
	s_mov_b32 s2, 0x42080000
	v_add_f32_e64 v160, v184, v68
	v_add_f32_e64 v161, v184, v69
	s_mov_b32 s3, 0x420c0000
	v_fma_f32 v162, v146, s2, v160
	v_fma_f32 v163, v147, s3, v161
	s_mov_b32 s2, 0x41000000
	v_add_f32_e64 v160, v184, v86
	v_add_f32_e64 v161, v184, v87
	s_mov_b32 s3, 0x41100000
	v_fma_f32 v160, v146, s2, v160
	v_fma_f32 v161, v147, s3, v161
	s_mov_b32 s2, 0x42200000
	v_add_f32_e64 v164, v184, v70
	v_add_f32_e64 v165, v184, v71
	s_mov_b32 s3, 0x42240000
	v_fma_f32 v164, v146, s2, v164
	v_fma_f32 v165, v147, s3, v165
	s_mov_b32 s2, 0x41200000
	v_add_f32_e64 v166, v184, v88
	v_add_f32_e64 v167, v184, v89
	s_mov_b32 s3, 0x41300000
	v_fma_f32 v166, v146, s2, v166
	v_fma_f32 v167, v147, s3, v167
	s_mov_b32 s2, 0x42280000
	v_add_f32_e64 v168, v184, v72
	v_add_f32_e64 v169, v184, v73
	s_mov_b32 s3, 0x422c0000
	v_fma_f32 v168, v146, s2, v168
	v_fma_f32 v169, v147, s3, v169
	s_mov_b32 s2, 0x41800000
	v_add_f32_e64 v170, v184, v90
	v_add_f32_e64 v171, v184, v91
	s_mov_b32 s3, 0x41880000
	v_fma_f32 v170, v146, s2, v170
	v_fma_f32 v171, v147, s3, v171
	s_mov_b32 s2, 0x42400000
	v_add_f32_e64 v172, v184, v74
	v_add_f32_e64 v173, v184, v75
	s_mov_b32 s3, 0x42440000
	v_fma_f32 v172, v146, s2, v172
	v_fma_f32 v173, v147, s3, v173
	s_mov_b32 s2, 0x41900000
	v_add_f32_e64 v174, v184, v92
	v_add_f32_e64 v175, v184, v93
	s_mov_b32 s3, 0x41980000
	v_fma_f32 v174, v146, s2, v174
	v_fma_f32 v175, v147, s3, v175
	s_mov_b32 s2, 0x42480000
	v_add_f32_e64 v178, v184, v76
	v_add_f32_e64 v179, v184, v77
	s_mov_b32 s3, 0x424c0000
	v_fma_f32 v178, v146, s2, v178
	v_fma_f32 v179, v147, s3, v179
	s_mov_b32 s2, 0x41c00000
	v_add_f32_e64 v180, v184, v94
	v_add_f32_e64 v181, v184, v95
	s_mov_b32 s3, 0x41c80000
	v_fma_f32 v180, v146, s2, v180
	v_fma_f32 v181, v147, s3, v181
	s_mov_b32 s2, 0x42600000
	v_add_f32_e64 v182, v184, v78
	v_add_f32_e64 v183, v184, v79
	s_mov_b32 s3, 0x42640000
	v_fma_f32 v182, v146, s2, v182
	v_fma_f32 v183, v147, s3, v183
	s_mov_b32 s2, 0x41d00000
	v_fma_f32 v199, -v146, v176, v80
	v_add_f32_e64 v185, v184, v97
	v_add_f32_e64 v184, v184, v96
	s_mov_b32 s3, 0x41d80000
	v_fma_f32 v200, -v146, v176, v81
	v_fma_f32 v82, 0, v146, v201
	v_fmac_f32_e32 v199, 0x42680000, v146
	v_fma_f32 v184, v146, s2, v184
	v_fma_f32 v185, v147, s3, v185
	v_fmac_f32_e32 v200, 0x426c0000, v146
	s_mov_b64 s[2:3], 0
; template <int MODE> DI void attn_h1(AttnCtx& c, const bf16x8 (&q)[8], f32x16 (&o)[4], f32x16& s0, f32x16& s1, ldsp lds, int kbuf, int bbuf, int tj, int lane) {
;     ...
;                 if (needmask) {
; #pragma unroll
;                     for (int e = 0; e < 16; ++e) {
;                         const float d0 = dbase - (float)(PS * (8 * (e >> 2) + (e & 3))), d1 = d0 - (float)(PS * 32);
;                         bool v0 = d0 >= 0.f, v1 = d1 >= 0.f;
;                         if (MODE == MD_WIN) { v0 = v0 && d0 < 512.f; v1 = v1 && d1 < 512.f; }
;                         if (MODE == MD_SEL) { v0 = v0 && selbit; v1 = v1 && selbit; }
;                         s0[e] = v0 ? s0[e] - c.slope2 * d0 : NINF;
;                         s1[e] = v1 ? s1[e] - c.slope2 * d1 : NINF;
;                     }
.LBB0_1068:
	s_andn2_b64 vcc, exec, s[2:3]
	s_cbranch_vccnz .LBB0_1070
	s_mov_b32 s2, -1.0
	s_mov_b32 s3, -2.0
	v_add_f32_e64 v160, v176, s2
	v_add_f32_e64 v161, v176, s3
	v_mov_b32_e32 v177, v160
	s_mov_b32 s8, 0xc2000000
	v_cmp_gt_u32_e32 vcc, s39, v198
	v_add_f32_e64 v148, v176, s8
	v_add_f32_e64 v149, v177, s8
	s_nop 0
	v_cndmask_b32_e32 v82, v230, v201, vcc
	v_cmp_le_f32_e32 vcc, 0, v148
	v_cmp_le_f32_e64 s[2:3], 0, v149
	v_cmp_gt_f32_e64 s[4:5], s33, v148
	v_cmp_gt_f32_e64 s[6:7], s33, v149
	s_and_b64 s[2:3], s[2:3], s[6:7]
	s_and_b64 vcc, vcc, s[4:5]
	v_fma_f32 v66, -v146, v148, v66
	v_fma_f32 v67, -v147, v149, v67
	v_cmp_gt_f32_e64 s[6:7], s33, v161
	v_cndmask_b32_e32 v154, v230, v66, vcc
	v_cndmask_b32_e64 v155, v230, v67, s[2:3]
	v_cmp_le_f32_e64 s[2:3], 0, v161
	v_mov_b32_e32 v66, v83
	v_mov_b32_e32 v67, v84
	v_cmp_le_f32_e32 vcc, 0, v160
	v_cmp_gt_f32_e64 s[4:5], s33, v160
	s_and_b64 s[2:3], s[2:3], s[6:7]
	v_fma_f32 v66, -v146, v160, v66
	v_fma_f32 v67, -v147, v161, v67
	s_and_b64 vcc, vcc, s[4:5]
	v_cndmask_b32_e64 v148, v230, v67, s[2:3]
	s_mov_b32 s2, 0xc0400000
	v_cndmask_b32_e32 v177, v230, v66, vcc
	s_mov_b32 s3, 0xc1000000
	v_add_f32_e64 v66, v176, s2
	v_add_f32_e64 v67, v176, s3
	v_pk_mov_b32 v[160:161], v[160:161], v[66:67] op_sel:[1,0]
	s_nop 0
	v_add_f32_e64 v160, v160, s8
	v_add_f32_e64 v161, v161, s8
	s_nop 0
	v_cmp_le_f32_e32 vcc, 0, v160
	v_cmp_le_f32_e64 s[2:3], 0, v161
	v_cmp_gt_f32_e64 s[4:5], s33, v160
	v_cmp_gt_f32_e64 s[6:7], s33, v161
	s_and_b64 s[2:3], s[2:3], s[6:7]
	s_and_b64 vcc, vcc, s[4:5]
	v_fma_f32 v68, -v146, v160, v68
	v_fma_f32 v69, -v147, v161, v69
	v_cmp_gt_f32_e64 s[6:7], s33, v67
	v_cndmask_b32_e32 v162, v230, v68, vcc
	v_cndmask_b32_e64 v163, v230, v69, s[2:3]
	v_cmp_le_f32_e64 s[2:3], 0, v67
	v_mov_b32_e32 v68, v85
	v_mov_b32_e32 v69, v86
	s_and_b64 s[2:3], s[2:3], s[6:7]
	v_fma_f32 v68, -v146, v66, v68
	v_fma_f32 v69, -v147, v67, v69
	v_cmp_le_f32_e32 vcc, 0, v66
	v_cmp_gt_f32_e64 s[4:5], s33, v66
	v_cndmask_b32_e64 v160, v230, v69, s[2:3]
	s_mov_b32 s2, 0xc1100000
	s_and_b64 vcc, vcc, s[4:5]
	s_mov_b32 s3, 0xc1200000
	v_cndmask_b32_e32 v149, v230, v68, vcc
	v_add_f32_e64 v68, v176, s2
	v_add_f32_e64 v69, v176, s3
	v_pk_mov_b32 v[66:67], v[66:67], v[68:69] op_sel:[1,0]
	s_nop 0
	v_add_f32_e64 v66, v66, s8
	v_add_f32_e64 v67, v67, s8
	s_nop 0
	v_cmp_le_f32_e32 vcc, 0, v66
	v_cmp_le_f32_e64 s[2:3], 0, v67
	v_cmp_gt_f32_e64 s[4:5], s33, v66
	v_cmp_gt_f32_e64 s[6:7], s33, v67
	s_and_b64 s[2:3], s[2:3], s[6:7]
	s_and_b64 vcc, vcc, s[4:5]
	v_fma_f32 v66, -v146, v66, v70
	v_fma_f32 v67, -v147, v67, v71
	v_cmp_gt_f32_e64 s[6:7], s33, v69
	v_cndmask_b32_e32 v164, v230, v66, vcc
	v_cndmask_b32_e64 v165, v230, v67, s[2:3]
	v_cmp_le_f32_e64 s[2:3], 0, v69
	v_mov_b32_e32 v66, v87
	v_mov_b32_e32 v67, v88
	s_and_b64 s[2:3], s[2:3], s[6:7]
	v_fma_f32 v66, -v146, v68, v66
	v_fma_f32 v67, -v147, v69, v67
	v_cmp_le_f32_e32 vcc, 0, v68
	v_cmp_gt_f32_e64 s[4:5], s33, v68
	v_cndmask_b32_e64 v166, v230, v67, s[2:3]
	s_mov_b32 s2, 0xc1300000
	s_and_b64 vcc, vcc, s[4:5]
	s_mov_b32 s3, 0xc1800000
	v_cndmask_b32_e32 v161, v230, v66, vcc
	v_add_f32_e64 v66, v176, s2
	v_add_f32_e64 v67, v176, s3
	v_pk_mov_b32 v[68:69], v[68:69], v[66:67] op_sel:[1,0]
	s_nop 0
	v_add_f32_e64 v68, v68, s8
	v_add_f32_e64 v69, v69, s8
	s_nop 0
	v_cmp_le_f32_e32 vcc, 0, v68
	v_cmp_le_f32_e64 s[2:3], 0, v69
	v_cmp_gt_f32_e64 s[4:5], s33, v68
	v_cmp_gt_f32_e64 s[6:7], s33, v69
	s_and_b64 s[2:3], s[2:3], s[6:7]
	s_and_b64 vcc, vcc, s[4:5]
	v_fma_f32 v68, -v146, v68, v72
	v_fma_f32 v69, -v147, v69, v73
	v_cmp_gt_f32_e64 s[6:7], s33, v67
	v_cndmask_b32_e32 v168, v230, v68, vcc
	v_cndmask_b32_e64 v169, v230, v69, s[2:3]
	v_cmp_le_f32_e64 s[2:3], 0, v67
	v_mov_b32_e32 v68, v89
	v_mov_b32_e32 v69, v90
; template <int MODE> DI void attn_h1(AttnCtx& c, const bf16x8 (&q)[8], f32x16 (&o)[4], f32x16& s0, f32x16& s1, ldsp lds, int kbuf, int bbuf, int tj, int lane) {
;     ...
;                 if (needmask) {
; #pragma unroll
;                     for (int e = 0; e < 16; ++e) {
;                         const float d0 = dbase - (float)(PS * (8 * (e >> 2) + (e & 3))), d1 = d0 - (float)(PS * 32);
;                         bool v0 = d0 >= 0.f, v1 = d1 >= 0.f;
;                         if (MODE == MD_WIN) { v0 = v0 && d0 < 512.f; v1 = v1 && d1 < 512.f; }
;                         if (MODE == MD_SEL) { v0 = v0 && selbit; v1 = v1 && selbit; }
;                         s0[e] = v0 ? s0[e] - c.slope2 * d0 : NINF;
;                         s1[e] = v1 ? s1[e] - c.slope2 * d1 : NINF;
;                     }
	s_and_b64 s[2:3], s[2:3], s[6:7]
	v_fma_f32 v68, -v146, v66, v68
	v_fma_f32 v69, -v147, v67, v69
	v_cmp_le_f32_e32 vcc, 0, v66
	v_cmp_gt_f32_e64 s[4:5], s33, v66
	v_cndmask_b32_e64 v170, v230, v69, s[2:3]
	s_mov_b32 s2, 0xc1880000
	s_and_b64 vcc, vcc, s[4:5]
	s_mov_b32 s3, 0xc1900000
	v_cndmask_b32_e32 v167, v230, v68, vcc
	v_add_f32_e64 v68, v176, s2
	v_add_f32_e64 v69, v176, s3
	v_pk_mov_b32 v[66:67], v[66:67], v[68:69] op_sel:[1,0]
	s_nop 0
	v_add_f32_e64 v66, v66, s8
	v_add_f32_e64 v67, v67, s8
	s_nop 0
	v_cmp_le_f32_e32 vcc, 0, v66
	v_cmp_le_f32_e64 s[2:3], 0, v67
	v_cmp_gt_f32_e64 s[4:5], s33, v66
	v_cmp_gt_f32_e64 s[6:7], s33, v67
	s_and_b64 s[2:3], s[2:3], s[6:7]
	s_and_b64 vcc, vcc, s[4:5]
	v_fma_f32 v66, -v146, v66, v74
	v_fma_f32 v67, -v147, v67, v75
	v_cmp_gt_f32_e64 s[6:7], s33, v69
	v_cndmask_b32_e32 v172, v230, v66, vcc
	v_cndmask_b32_e64 v173, v230, v67, s[2:3]
	v_cmp_le_f32_e64 s[2:3], 0, v69
	v_mov_b32_e32 v66, v91
	v_mov_b32_e32 v67, v92
	s_and_b64 s[2:3], s[2:3], s[6:7]
	v_fma_f32 v66, -v146, v68, v66
	v_fma_f32 v67, -v147, v69, v67
	v_cmp_le_f32_e32 vcc, 0, v68
	v_cmp_gt_f32_e64 s[4:5], s33, v68
	v_cndmask_b32_e64 v174, v230, v67, s[2:3]
	s_mov_b32 s2, 0xc1980000
	s_and_b64 vcc, vcc, s[4:5]
	s_mov_b32 s3, 0xc1c00000
	v_cndmask_b32_e32 v171, v230, v66, vcc
	v_add_f32_e64 v66, v176, s2
	v_add_f32_e64 v67, v176, s3
	v_pk_mov_b32 v[68:69], v[68:69], v[66:67] op_sel:[1,0]
	s_nop 0
	v_add_f32_e64 v68, v68, s8
	v_add_f32_e64 v69, v69, s8
	s_nop 0
	v_cmp_le_f32_e32 vcc, 0, v68
	v_cmp_le_f32_e64 s[2:3], 0, v69
	v_cmp_gt_f32_e64 s[4:5], s33, v68
	v_cmp_gt_f32_e64 s[6:7], s33, v69
	s_and_b64 s[2:3], s[2:3], s[6:7]
	s_and_b64 vcc, vcc, s[4:5]
	v_fma_f32 v68, -v146, v68, v76
	v_fma_f32 v69, -v147, v69, v77
	v_cmp_gt_f32_e64 s[6:7], s33, v67
	v_cndmask_b32_e32 v178, v230, v68, vcc
	v_cndmask_b32_e64 v179, v230, v69, s[2:3]
	v_cmp_le_f32_e64 s[2:3], 0, v67
	v_mov_b32_e32 v68, v93
	v_mov_b32_e32 v69, v94
	s_and_b64 s[2:3], s[2:3], s[6:7]
	v_fma_f32 v68, -v146, v66, v68
	v_fma_f32 v69, -v147, v67, v69
	v_cmp_le_f32_e32 vcc, 0, v66
	v_cmp_gt_f32_e64 s[4:5], s33, v66
	v_cndmask_b32_e64 v180, v230, v69, s[2:3]
	s_mov_b32 s2, 0xc1c80000
	s_and_b64 vcc, vcc, s[4:5]
	s_mov_b32 s3, 0xc1d00000
	v_cndmask_b32_e32 v175, v230, v68, vcc
	v_add_f32_e64 v68, v176, s2
	v_add_f32_e64 v69, v176, s3
	v_pk_mov_b32 v[66:67], v[66:67], v[68:69] op_sel:[1,0]
	v_add_f32_e32 v70, 0xc2000000, v69
	v_add_f32_e64 v66, v66, s8
	v_add_f32_e64 v67, v67, s8
	v_cmp_gt_f32_e64 s[8:9], s33, v69
	v_cmp_le_f32_e32 vcc, 0, v66
	v_cmp_le_f32_e64 s[2:3], 0, v67
	v_cmp_gt_f32_e64 s[4:5], s33, v66
	v_cmp_gt_f32_e64 s[6:7], s33, v67
	s_and_b64 s[2:3], s[2:3], s[6:7]
	s_and_b64 vcc, vcc, s[4:5]
	v_fma_f32 v66, -v146, v66, v78
	v_fma_f32 v67, -v147, v67, v79
	v_cmp_gt_f32_e64 s[6:7], s33, v68
	v_cndmask_b32_e32 v182, v230, v66, vcc
	v_cndmask_b32_e64 v183, v230, v67, s[2:3]
	v_cmp_le_f32_e32 vcc, 0, v70
	v_cmp_gt_f32_e64 s[2:3], s33, v70
	s_and_b64 vcc, vcc, s[2:3]
	v_cmp_le_f32_e64 s[2:3], 0, v68
	v_mov_b32_e32 v66, v95
	v_mov_b32_e32 v67, v96
	s_and_b64 s[2:3], s[2:3], s[6:7]
	v_fma_f32 v66, -v146, v68, v66
	v_fma_f32 v67, -v147, v69, v67
	v_cmp_le_f32_e64 s[4:5], 0, v69
	v_cndmask_b32_e64 v181, v230, v66, s[2:3]
	v_fma_f32 v66, -v146, v70, v80
	s_and_b64 s[4:5], s[4:5], s[8:9]
	v_cndmask_b32_e32 v199, v230, v66, vcc
	v_add_f32_e32 v66, 0xc1d80000, v176
	v_cndmask_b32_e64 v184, v230, v67, s[4:5]
	v_add_f32_e32 v67, 0xc2000000, v66
	v_cmp_le_f32_e32 vcc, 0, v66
	v_cmp_gt_f32_e64 s[4:5], s33, v66
	v_cmp_le_f32_e64 s[2:3], 0, v67
	s_and_b64 vcc, vcc, s[4:5]
	v_cmp_gt_f32_e64 s[4:5], s33, v67
	v_fma_f32 v66, -v146, v66, v97
	s_and_b64 s[2:3], s[2:3], s[4:5]
	v_cndmask_b32_e32 v185, v230, v66, vcc
	v_fma_f32 v66, -v146, v67, v81
	v_cndmask_b32_e64 v200, v230, v66, s[2:3]
